# attention: the four staging loads of a tile spread over QK^T slots 4/12/20/28 (was 2/6/10/14)
# speedup vs baseline: 1.0104x; 1.0097x over previous
; #define SBAR() __builtin_amdgcn_sched_barrier(0)
; #define SLOAD(i, k0) do { sr_[i].vs0 = St::ld8(&Vh[(long)((k0) + sr) * LDK + sc]); sr_[i].vs1 = St::ld8(&Vh[(long)((k0) + 32 + sr) * LDK + sc]); \
;     sr_[i].ks0 = St::ld8(&Kh[(long)((k0) + sr) * LDK + sc]); sr_[i].ks1 = St::ld8(&Kh[(long)((k0) + 32 + sr) * LDK + sc]); } while (0)
; __device__ __forceinline__ void finishSM(f32x16& p0, f32x16& p1, float& l_reg, bf16x8& pa0, bf16x8& pa1, bf16x8& pa2, bf16x8& pa3) {
;   for (int r = 0; r < 16; ++r) p1[r] = __builtin_amdgcn_exp2f(p1[r]);
;   float ps = 0; for (int r = 0; r < 16; ++r) ps += p0[r]; for (int r = 0; r < 16; ++r) ps += p1[r];
;   { auto rr = __builtin_amdgcn_permlane32_swap(__float_as_uint(ps), __float_as_uint(ps), false, false);
;     ps = __uint_as_float(rr[0]) + __uint_as_float(rr[1]); }
;   l_reg += ps;
;     ...
;   PK4(p0, 0, pa0); PK4(p0, 8, pa1); PK4(p1, 0, pa2); PK4(p1, 8, pa3);
;     ...
; }
; __device__ __forceinline__ void qkt(f32x16& p0, f32x16& p1, const bf16* Ks, const bf16x8* qr, int r32, int hi, const f32x16& negm) {
; #pragma unroll
;   for (int d0 = 0; d0 < 8; ++d0) { int cb = (d0 * 16 + hi * 8) * 2;
;     bf16x8 b0 = *reinterpret_cast<const bf16x8*>((const char*)Ks + KSWZ(r32, cb));
;     bf16x8 b1 = *reinterpret_cast<const bf16x8*>((const char*)Ks + KSWZ(32 + r32, cb));
;     if (d0 == 0) { p0 = __builtin_amdgcn_mfma_f32_32x32x16_bf16(b0, qr[0], negm, 0, 0, 0); p1 = __builtin_amdgcn_mfma_f32_32x32x16_bf16(b1, qr[0], negm, 0, 0, 0); }
;     else { p0 = __builtin_amdgcn_mfma_f32_32x32x16_bf16(b0, qr[d0], p0, 0, 0, 0); p1 = __builtin_amdgcn_mfma_f32_32x32x16_bf16(b1, qr[d0], p1, 0, 0, 0); } }
; }
; template <typename TQ> ...
;     ...
;   for (int j = 1; j + 1 < NT; j += 2) {
;     SBAR(); SLOAD(SO, (j + SDEPTH) * KVBLK); SBAR();
;     qkt(pB0, pB1, (bf16*)((char*)K_lds + SHM_K), qr, r32, hi, negm);
;     finishSM(pA0, pA1, l_reg, pa0, pa1, pa2, pa3); SBAR();
;     pv_d0(o, vb0, pa0, pa1, pa2, pa3); partialSM(pB0, pB1, mC);
.Lattn_loop:
	s_barrier
	s_waitcnt lgkmcnt(3)
	v_mfma_f32_16x16x32_bf16 v[114:117], v[178:181], v[146:149], v[2:5]
	v_add_f32_e32 v250, v82, v250
	s_add_u32 s98, s98, 0x8000
	s_addc_u32 s99, s99, 0
	s_add_u32 s100, s100, 0x8000
	s_addc_u32 s101, s101, 0
	v_mfma_f32_16x16x32_bf16 v[118:121], v[178:181], v[162:165], v[2:5]
	ds_read_b128 v[178:181], v235 offset:16384
	v_add_f32_e32 v250, v83, v250
	v_add_f32_e32 v250, v84, v250
	s_waitcnt lgkmcnt(3)
	v_mfma_f32_16x16x32_bf16 v[122:125], v[182:185], v[146:149], v[2:5]
	v_add_f32_e32 v250, v85, v250
	v_mfma_f32_16x16x32_bf16 v[126:129], v[182:185], v[162:165], v[2:5]
	ds_read_b128 v[182:185], v235 offset:20480
	v_add_f32_e32 v250, v90, v250
	v_add_f32_e32 v250, v91, v250
	s_waitcnt lgkmcnt(3)
	v_mfma_f32_16x16x32_bf16 v[130:133], v[186:189], v[146:149], v[2:5]
	v_add_f32_e32 v250, v92, v250
	s_add_u32 m0, s79, 0
	s_nop 0
	global_load_lds_dwordx4 v246, s[98:99]
	v_mfma_f32_16x16x32_bf16 v[134:137], v[186:189], v[162:165], v[2:5]
	ds_read_b128 v[186:189], v235 offset:24576
	v_add_f32_e32 v250, v93, v250
	v_cvt_pk_bf16_f32 v82, v82, v83
	s_waitcnt lgkmcnt(3)
	v_mfma_f32_16x16x32_bf16 v[138:141], v[190:193], v[146:149], v[2:5]
	v_cvt_pk_bf16_f32 v83, v84, v85
	v_mfma_f32_16x16x32_bf16 v[142:145], v[190:193], v[162:165], v[2:5]
	ds_read_b128 v[190:193], v235 offset:28672
	v_cvt_pk_bf16_f32 v84, v90, v91
	v_cvt_pk_bf16_f32 v85, v92, v93
	s_waitcnt lgkmcnt(3)
	v_mfma_f32_16x16x32_bf16 v[114:117], v[178:181], v[150:153], v[114:117]
	v_add_f32_e32 v251, v86, v251
	v_mfma_f32_16x16x32_bf16 v[118:121], v[178:181], v[166:169], v[118:121]
	ds_read_b128 v[178:181], v236 offset:16384
	v_add_f32_e32 v251, v87, v251
	v_add_f32_e32 v251, v88, v251
	s_waitcnt lgkmcnt(3)
	v_mfma_f32_16x16x32_bf16 v[122:125], v[182:185], v[150:153], v[122:125]
	v_add_f32_e32 v251, v89, v251
	v_mfma_f32_16x16x32_bf16 v[126:129], v[182:185], v[166:169], v[126:129]
	ds_read_b128 v[182:185], v236 offset:20480
	v_add_f32_e32 v251, v94, v251
	v_add_f32_e32 v251, v95, v251
	s_waitcnt lgkmcnt(3)
	v_mfma_f32_16x16x32_bf16 v[130:133], v[186:189], v[150:153], v[130:133]
	v_add_f32_e32 v251, v96, v251
	s_add_u32 m0, s79, 1024
	s_nop 0
	global_load_lds_dwordx4 v247, s[98:99]
	v_mfma_f32_16x16x32_bf16 v[134:137], v[186:189], v[166:169], v[134:137]
	ds_read_b128 v[186:189], v236 offset:24576
	v_add_f32_e32 v251, v97, v251
	v_cvt_pk_bf16_f32 v86, v86, v87
	s_waitcnt lgkmcnt(3)
	v_mfma_f32_16x16x32_bf16 v[138:141], v[190:193], v[150:153], v[138:141]
	v_cvt_pk_bf16_f32 v87, v88, v89
	v_mfma_f32_16x16x32_bf16 v[142:145], v[190:193], v[166:169], v[142:145]
	ds_read_b128 v[190:193], v236 offset:28672
	v_cvt_pk_bf16_f32 v88, v94, v95
	v_cvt_pk_bf16_f32 v89, v96, v97
	s_waitcnt lgkmcnt(3)
	v_mfma_f32_16x16x32_bf16 v[114:117], v[178:181], v[154:157], v[114:117]
	v_add_f32_e32 v250, v98, v250
	v_mfma_f32_16x16x32_bf16 v[118:121], v[178:181], v[170:173], v[118:121]
	ds_read_b128 v[178:181], v237 offset:16384
	v_add_f32_e32 v250, v99, v250
	v_add_f32_e32 v250, v100, v250
	s_waitcnt lgkmcnt(3)
	v_mfma_f32_16x16x32_bf16 v[122:125], v[182:185], v[154:157], v[122:125]
	v_add_f32_e32 v250, v101, v250
	v_mfma_f32_16x16x32_bf16 v[126:129], v[182:185], v[170:173], v[126:129]
	ds_read_b128 v[182:185], v237 offset:20480
	v_add_f32_e32 v250, v106, v250
	v_add_f32_e32 v250, v107, v250
	s_waitcnt lgkmcnt(3)
	v_mfma_f32_16x16x32_bf16 v[130:133], v[186:189], v[154:157], v[130:133]
	v_add_f32_e32 v250, v108, v250
	s_add_u32 m0, s80, 49152
	s_nop 0
	global_load_lds_dwordx4 v248, s[100:101]
	ds_read_b64_tr_b16 v[202:203], v238 offset:0
	ds_read_b64_tr_b16 v[204:205], v238 offset:4096
	v_mfma_f32_16x16x32_bf16 v[134:137], v[186:189], v[170:173], v[134:137]
	ds_read_b128 v[186:189], v237 offset:24576
	v_add_f32_e32 v250, v109, v250
	v_cvt_pk_bf16_f32 v98, v98, v99
	s_waitcnt lgkmcnt(5)
	v_mfma_f32_16x16x32_bf16 v[138:141], v[190:193], v[154:157], v[138:141]
	v_cvt_pk_bf16_f32 v99, v100, v101
	ds_read_b64_tr_b16 v[206:207], v239 offset:0
	ds_read_b64_tr_b16 v[208:209], v239 offset:4096
	v_mfma_f32_16x16x32_bf16 v[142:145], v[190:193], v[170:173], v[142:145]
	ds_read_b128 v[190:193], v237 offset:28672
	v_cvt_pk_bf16_f32 v100, v106, v107
	v_cvt_pk_bf16_f32 v101, v108, v109
	s_waitcnt lgkmcnt(7)
	v_mfma_f32_16x16x32_bf16 v[114:117], v[178:181], v[158:161], v[114:117]
	v_add_f32_e32 v251, v102, v251
	ds_read_b64_tr_b16 v[210:211], v240 offset:0
	ds_read_b64_tr_b16 v[212:213], v240 offset:4096
	v_mfma_f32_16x16x32_bf16 v[118:121], v[178:181], v[174:177], v[118:121]
	v_add_f32_e32 v251, v103, v251
	v_add_f32_e32 v251, v104, v251
	s_waitcnt lgkmcnt(8)
	v_mfma_f32_16x16x32_bf16 v[122:125], v[182:185], v[158:161], v[122:125]
	v_add_f32_e32 v251, v105, v251
	ds_read_b64_tr_b16 v[214:215], v241 offset:0
	ds_read_b64_tr_b16 v[216:217], v241 offset:4096
	v_mfma_f32_16x16x32_bf16 v[126:129], v[182:185], v[174:177], v[126:129]
	v_add_f32_e32 v251, v110, v251
	v_add_f32_e32 v251, v111, v251
	s_waitcnt lgkmcnt(7)
	v_mfma_f32_16x16x32_bf16 v[130:133], v[186:189], v[158:161], v[130:133]
	v_add_f32_e32 v251, v112, v251
	s_add_u32 m0, s80, 50176
	s_nop 0
	global_load_lds_dwordx4 v249, s[100:101]
	ds_read_b64_tr_b16 v[218:219], v242 offset:0
	ds_read_b64_tr_b16 v[220:221], v242 offset:4096
	v_mfma_f32_16x16x32_bf16 v[134:137], v[186:189], v[174:177], v[134:137]
	v_add_f32_e32 v251, v113, v251
	v_cvt_pk_bf16_f32 v102, v102, v103
	s_waitcnt lgkmcnt(6)
; #define SBAR() __builtin_amdgcn_sched_barrier(0)
; __device__ __forceinline__ void partialSM(f32x16& p0, f32x16& p1, float mC) {
;   (void)mC; (void)p1;
;   for (int r = 0; r < 16; ++r) p0[r] = __builtin_amdgcn_exp2f(p0[r]);
; }
; template <int OFF> __device__ __forceinline__ s16x4 tr_read(int vb) {
;   s16x4 r; asm volatile("ds_read_b64_tr_b16 %0, %1 offset:%2" : "=&v"(r) : "v"(vb), "i"(OFF) : "memory"); return r;
; }
; template <int D0> __device__ __forceinline__ void pv_one(f32x16& od, int vb, bf16x8 pa0, bf16x8 pa1, bf16x8 pa2, bf16x8 pa3) {
;   const s16x4 l0 = tr_read<v_rd_off(D0, 0, 0)>(vb), h0 = tr_read<v_rd_off(D0, 0, 1)>(vb), l1 = tr_read<v_rd_off(D0, 1, 0)>(vb), h1 = tr_read<v_rd_off(D0, 1, 1)>(vb);
;   const s16x4 l2 = tr_read<v_rd_off(D0, 2, 0)>(vb), h2 = tr_read<v_rd_off(D0, 2, 1)>(vb), l3 = tr_read<v_rd_off(D0, 3, 0)>(vb), h3 = tr_read<v_rd_off(D0, 3, 1)>(vb);
;   asm volatile("s_waitcnt lgkmcnt(0)" ::: "memory"); SBAR();
;     ...
;   od = __builtin_amdgcn_mfma_f32_32x32x16_bf16(pa0, PK(l0, h0), od, 0, 0, 0);
;   od = __builtin_amdgcn_mfma_f32_32x32x16_bf16(pa1, PK(l1, h1), od, 0, 0, 0);
;   od = __builtin_amdgcn_mfma_f32_32x32x16_bf16(pa2, PK(l2, h2), od, 0, 0, 0);
;   od = __builtin_amdgcn_mfma_f32_32x32x16_bf16(pa3, PK(l3, h3), od, 0, 0, 0);
;     ...
; }
; __device__ __forceinline__ void pv_d0(f32x16* o, int vb, bf16x8 pa0, bf16x8 pa1, bf16x8 pa2, bf16x8 pa3) {
;   pv_one<0>(o[0], vb, pa0, pa1, pa2, pa3); pv_one<1>(o[1], vb, pa0, pa1, pa2, pa3); pv_one<2>(o[2], vb, pa0, pa1, pa2, pa3); pv_one<3>(o[3], vb, pa0, pa1, pa2, pa3);
	v_mfma_f32_16x16x32_bf16 v[138:141], v[190:193], v[158:161], v[138:141]
	v_cvt_pk_bf16_f32 v103, v104, v105
	ds_read_b64_tr_b16 v[222:223], v243 offset:0
	ds_read_b64_tr_b16 v[224:225], v243 offset:4096
	v_mfma_f32_16x16x32_bf16 v[142:145], v[190:193], v[174:177], v[142:145]
	v_cvt_pk_bf16_f32 v104, v110, v111
	v_cvt_pk_bf16_f32 v105, v112, v113
	v_mfma_f32_16x16x32_bf16 v[18:21], v[202:205], v[82:85], v[18:21]
	v_exp_f32_e32 v114, v114
	v_mfma_f32_16x16x32_bf16 v[22:25], v[202:205], v[86:89], v[22:25]
	ds_read_b64_tr_b16 v[202:203], v244 offset:0
	ds_read_b64_tr_b16 v[204:205], v244 offset:4096
	v_exp_f32_e32 v115, v115
	v_mfma_f32_16x16x32_bf16 v[26:29], v[206:209], v[82:85], v[26:29]
	v_exp_f32_e32 v116, v116
	v_mfma_f32_16x16x32_bf16 v[30:33], v[206:209], v[86:89], v[30:33]
	ds_read_b64_tr_b16 v[206:207], v245 offset:0
	ds_read_b64_tr_b16 v[208:209], v245 offset:4096
	v_exp_f32_e32 v117, v117
	s_waitcnt lgkmcnt(10)
	v_mfma_f32_16x16x32_bf16 v[34:37], v[210:213], v[82:85], v[34:37]
	v_exp_f32_e32 v118, v118
	v_mfma_f32_16x16x32_bf16 v[38:41], v[210:213], v[86:89], v[38:41]
	ds_read_b64_tr_b16 v[210:211], v238 offset:8192
	ds_read_b64_tr_b16 v[212:213], v238 offset:12288
	v_exp_f32_e32 v119, v119
	s_waitcnt lgkmcnt(10)
	v_mfma_f32_16x16x32_bf16 v[42:45], v[214:217], v[82:85], v[42:45]
	v_exp_f32_e32 v120, v120
	v_mfma_f32_16x16x32_bf16 v[46:49], v[214:217], v[86:89], v[46:49]
	ds_read_b64_tr_b16 v[214:215], v239 offset:8192
	ds_read_b64_tr_b16 v[216:217], v239 offset:12288
	v_exp_f32_e32 v121, v121
	s_waitcnt lgkmcnt(10)
	v_mfma_f32_16x16x32_bf16 v[50:53], v[218:221], v[82:85], v[50:53]
	v_exp_f32_e32 v122, v122
	v_mfma_f32_16x16x32_bf16 v[54:57], v[218:221], v[86:89], v[54:57]
	ds_read_b64_tr_b16 v[218:219], v240 offset:8192
	ds_read_b64_tr_b16 v[220:221], v240 offset:12288
	v_exp_f32_e32 v123, v123
	s_waitcnt lgkmcnt(10)
	v_mfma_f32_16x16x32_bf16 v[58:61], v[222:225], v[82:85], v[58:61]
	v_exp_f32_e32 v124, v124
	v_mfma_f32_16x16x32_bf16 v[62:65], v[222:225], v[86:89], v[62:65]
	ds_read_b64_tr_b16 v[222:223], v241 offset:8192
	ds_read_b64_tr_b16 v[224:225], v241 offset:12288
	v_exp_f32_e32 v125, v125
	s_waitcnt lgkmcnt(10)
	v_mfma_f32_16x16x32_bf16 v[66:69], v[202:205], v[82:85], v[66:69]
	v_exp_f32_e32 v126, v126
	v_mfma_f32_16x16x32_bf16 v[70:73], v[202:205], v[86:89], v[70:73]
	ds_read_b64_tr_b16 v[202:203], v242 offset:8192
	ds_read_b64_tr_b16 v[204:205], v242 offset:12288
	v_exp_f32_e32 v127, v127
	s_waitcnt lgkmcnt(10)
	v_mfma_f32_16x16x32_bf16 v[74:77], v[206:209], v[82:85], v[74:77]
	v_exp_f32_e32 v128, v128
	v_mfma_f32_16x16x32_bf16 v[78:81], v[206:209], v[86:89], v[78:81]
	ds_read_b64_tr_b16 v[206:207], v243 offset:8192
	ds_read_b64_tr_b16 v[208:209], v243 offset:12288
	v_exp_f32_e32 v129, v129
	s_waitcnt lgkmcnt(10)
	v_mfma_f32_16x16x32_bf16 v[18:21], v[210:213], v[98:101], v[18:21]
	v_exp_f32_e32 v130, v130
	v_mfma_f32_16x16x32_bf16 v[22:25], v[210:213], v[102:105], v[22:25]
	ds_read_b64_tr_b16 v[210:211], v244 offset:8192
	ds_read_b64_tr_b16 v[212:213], v244 offset:12288
	v_exp_f32_e32 v131, v131
	s_waitcnt lgkmcnt(10)
	v_mfma_f32_16x16x32_bf16 v[26:29], v[214:217], v[98:101], v[26:29]
	v_exp_f32_e32 v132, v132
	v_mfma_f32_16x16x32_bf16 v[30:33], v[214:217], v[102:105], v[30:33]
	ds_read_b64_tr_b16 v[214:215], v245 offset:8192
	ds_read_b64_tr_b16 v[216:217], v245 offset:12288
	v_exp_f32_e32 v133, v133
	s_waitcnt lgkmcnt(10)
	v_mfma_f32_16x16x32_bf16 v[34:37], v[218:221], v[98:101], v[34:37]
	v_exp_f32_e32 v134, v134
	v_mfma_f32_16x16x32_bf16 v[38:41], v[218:221], v[102:105], v[38:41]
	v_exp_f32_e32 v135, v135
	s_waitcnt lgkmcnt(8)
	v_mfma_f32_16x16x32_bf16 v[42:45], v[222:225], v[98:101], v[42:45]
	v_exp_f32_e32 v136, v136
	v_mfma_f32_16x16x32_bf16 v[46:49], v[222:225], v[102:105], v[46:49]
	v_exp_f32_e32 v137, v137
	s_waitcnt lgkmcnt(6)
	v_mfma_f32_16x16x32_bf16 v[50:53], v[202:205], v[98:101], v[50:53]
	v_exp_f32_e32 v138, v138
	ds_read_b128 v[178:181], v234 offset:32768
	v_mfma_f32_16x16x32_bf16 v[54:57], v[202:205], v[102:105], v[54:57]
	v_exp_f32_e32 v139, v139
	s_waitcnt lgkmcnt(5)
	v_mfma_f32_16x16x32_bf16 v[58:61], v[206:209], v[98:101], v[58:61]
	v_exp_f32_e32 v140, v140
	ds_read_b128 v[182:185], v234 offset:36864
	v_mfma_f32_16x16x32_bf16 v[62:65], v[206:209], v[102:105], v[62:65]
	v_exp_f32_e32 v141, v141
	s_waitcnt lgkmcnt(4)
	v_mfma_f32_16x16x32_bf16 v[66:69], v[210:213], v[98:101], v[66:69]
	v_exp_f32_e32 v142, v142
	ds_read_b128 v[186:189], v234 offset:40960
	v_mfma_f32_16x16x32_bf16 v[70:73], v[210:213], v[102:105], v[70:73]
	v_exp_f32_e32 v143, v143
	s_waitcnt lgkmcnt(3)
	v_mfma_f32_16x16x32_bf16 v[74:77], v[214:217], v[98:101], v[74:77]
	v_exp_f32_e32 v144, v144
	ds_read_b128 v[190:193], v234 offset:45056
	v_mfma_f32_16x16x32_bf16 v[78:81], v[214:217], v[102:105], v[78:81]
	v_exp_f32_e32 v145, v145
	s_waitcnt vmcnt(4)
	s_barrier
; #define SBAR() __builtin_amdgcn_sched_barrier(0)
; #define SLOAD(i, k0) do { sr_[i].vs0 = St::ld8(&Vh[(long)((k0) + sr) * LDK + sc]); sr_[i].vs1 = St::ld8(&Vh[(long)((k0) + 32 + sr) * LDK + sc]); \
;     sr_[i].ks0 = St::ld8(&Kh[(long)((k0) + sr) * LDK + sc]); sr_[i].ks1 = St::ld8(&Kh[(long)((k0) + 32 + sr) * LDK + sc]); } while (0)
; __device__ __forceinline__ void finishSM(f32x16& p0, f32x16& p1, float& l_reg, bf16x8& pa0, bf16x8& pa1, bf16x8& pa2, bf16x8& pa3) {
;   for (int r = 0; r < 16; ++r) p1[r] = __builtin_amdgcn_exp2f(p1[r]);
;   float ps = 0; for (int r = 0; r < 16; ++r) ps += p0[r]; for (int r = 0; r < 16; ++r) ps += p1[r];
;   { auto rr = __builtin_amdgcn_permlane32_swap(__float_as_uint(ps), __float_as_uint(ps), false, false);
;     ps = __uint_as_float(rr[0]) + __uint_as_float(rr[1]); }
;   l_reg += ps;
;     ...
;   PK4(p0, 0, pa0); PK4(p0, 8, pa1); PK4(p1, 0, pa2); PK4(p1, 8, pa3);
;     ...
; }
; __device__ __forceinline__ void qkt(f32x16& p0, f32x16& p1, const bf16* Ks, const bf16x8* qr, int r32, int hi, const f32x16& negm) {
; #pragma unroll
;   for (int d0 = 0; d0 < 8; ++d0) { int cb = (d0 * 16 + hi * 8) * 2;
;     bf16x8 b0 = *reinterpret_cast<const bf16x8*>((const char*)Ks + KSWZ(r32, cb));
;     bf16x8 b1 = *reinterpret_cast<const bf16x8*>((const char*)Ks + KSWZ(32 + r32, cb));
;     if (d0 == 0) { p0 = __builtin_amdgcn_mfma_f32_32x32x16_bf16(b0, qr[0], negm, 0, 0, 0); p1 = __builtin_amdgcn_mfma_f32_32x32x16_bf16(b1, qr[0], negm, 0, 0, 0); }
;     else { p0 = __builtin_amdgcn_mfma_f32_32x32x16_bf16(b0, qr[d0], p0, 0, 0, 0); p1 = __builtin_amdgcn_mfma_f32_32x32x16_bf16(b1, qr[d0], p1, 0, 0, 0); } }
; }
; template <typename TQ> ...
;     ...
;   for (int j = 1; j + 1 < NT; j += 2) {
;     SBAR(); SLOAD(SO, (j + SDEPTH) * KVBLK); SBAR();
;     qkt(pB0, pB1, (bf16*)((char*)K_lds + SHM_K), qr, r32, hi, negm);
;     finishSM(pA0, pA1, l_reg, pa0, pa1, pa2, pa3); SBAR();
;     pv_d0(o, vb0, pa0, pa1, pa2, pa3); partialSM(pB0, pB1, mC);
	s_waitcnt lgkmcnt(3)
	v_mfma_f32_16x16x32_bf16 v[82:85], v[178:181], v[146:149], v[2:5]
	v_add_f32_e32 v250, v114, v250
	s_add_u32 s98, s98, 0x8000
	s_addc_u32 s99, s99, 0
	s_add_u32 s100, s100, 0x8000
	s_addc_u32 s101, s101, 0
	v_mfma_f32_16x16x32_bf16 v[86:89], v[178:181], v[162:165], v[2:5]
	ds_read_b128 v[178:181], v235 offset:32768
	v_add_f32_e32 v250, v115, v250
	v_add_f32_e32 v250, v116, v250
	s_waitcnt lgkmcnt(3)
	v_mfma_f32_16x16x32_bf16 v[90:93], v[182:185], v[146:149], v[2:5]
	v_add_f32_e32 v250, v117, v250
	v_mfma_f32_16x16x32_bf16 v[94:97], v[182:185], v[162:165], v[2:5]
	ds_read_b128 v[182:185], v235 offset:36864
	v_add_f32_e32 v250, v122, v250
	v_add_f32_e32 v250, v123, v250
	s_waitcnt lgkmcnt(3)
	v_mfma_f32_16x16x32_bf16 v[98:101], v[186:189], v[146:149], v[2:5]
	v_add_f32_e32 v250, v124, v250
	s_add_u32 m0, s79, 16384
	s_nop 0
	global_load_lds_dwordx4 v246, s[98:99]
	v_mfma_f32_16x16x32_bf16 v[102:105], v[186:189], v[162:165], v[2:5]
	ds_read_b128 v[186:189], v235 offset:40960
	v_add_f32_e32 v250, v125, v250
	v_cvt_pk_bf16_f32 v114, v114, v115
	s_waitcnt lgkmcnt(3)
	v_mfma_f32_16x16x32_bf16 v[106:109], v[190:193], v[146:149], v[2:5]
	v_cvt_pk_bf16_f32 v115, v116, v117
	v_mfma_f32_16x16x32_bf16 v[110:113], v[190:193], v[162:165], v[2:5]
	ds_read_b128 v[190:193], v235 offset:45056
	v_cvt_pk_bf16_f32 v116, v122, v123
	v_cvt_pk_bf16_f32 v117, v124, v125
	s_waitcnt lgkmcnt(3)
	v_mfma_f32_16x16x32_bf16 v[82:85], v[178:181], v[150:153], v[82:85]
	v_add_f32_e32 v251, v118, v251
	v_mfma_f32_16x16x32_bf16 v[86:89], v[178:181], v[166:169], v[86:89]
	ds_read_b128 v[178:181], v236 offset:32768
	v_add_f32_e32 v251, v119, v251
	v_add_f32_e32 v251, v120, v251
	s_waitcnt lgkmcnt(3)
	v_mfma_f32_16x16x32_bf16 v[90:93], v[182:185], v[150:153], v[90:93]
	v_add_f32_e32 v251, v121, v251
	v_mfma_f32_16x16x32_bf16 v[94:97], v[182:185], v[166:169], v[94:97]
	ds_read_b128 v[182:185], v236 offset:36864
	v_add_f32_e32 v251, v126, v251
	v_add_f32_e32 v251, v127, v251
	s_waitcnt lgkmcnt(3)
	v_mfma_f32_16x16x32_bf16 v[98:101], v[186:189], v[150:153], v[98:101]
	v_add_f32_e32 v251, v128, v251
	s_add_u32 m0, s79, 17408
	s_nop 0
	global_load_lds_dwordx4 v247, s[98:99]
	v_mfma_f32_16x16x32_bf16 v[102:105], v[186:189], v[166:169], v[102:105]
	ds_read_b128 v[186:189], v236 offset:40960
	v_add_f32_e32 v251, v129, v251
	v_cvt_pk_bf16_f32 v118, v118, v119
	s_waitcnt lgkmcnt(3)
	v_mfma_f32_16x16x32_bf16 v[106:109], v[190:193], v[150:153], v[106:109]
	v_cvt_pk_bf16_f32 v119, v120, v121
	v_mfma_f32_16x16x32_bf16 v[110:113], v[190:193], v[166:169], v[110:113]
	ds_read_b128 v[190:193], v236 offset:45056
	v_cvt_pk_bf16_f32 v120, v126, v127
	v_cvt_pk_bf16_f32 v121, v128, v129
	s_waitcnt lgkmcnt(3)
	v_mfma_f32_16x16x32_bf16 v[82:85], v[178:181], v[154:157], v[82:85]
	v_add_f32_e32 v250, v130, v250
	v_mfma_f32_16x16x32_bf16 v[86:89], v[178:181], v[170:173], v[86:89]
	ds_read_b128 v[178:181], v237 offset:32768
	v_add_f32_e32 v250, v131, v250
	v_add_f32_e32 v250, v132, v250
	s_waitcnt lgkmcnt(3)
	v_mfma_f32_16x16x32_bf16 v[90:93], v[182:185], v[154:157], v[90:93]
	v_add_f32_e32 v250, v133, v250
	v_mfma_f32_16x16x32_bf16 v[94:97], v[182:185], v[170:173], v[94:97]
	ds_read_b128 v[182:185], v237 offset:36864
	v_add_f32_e32 v250, v138, v250
	v_add_f32_e32 v250, v139, v250
	s_waitcnt lgkmcnt(3)
	v_mfma_f32_16x16x32_bf16 v[98:101], v[186:189], v[154:157], v[98:101]
	v_add_f32_e32 v250, v140, v250
	s_add_u32 m0, s80, 0
	s_nop 0
	global_load_lds_dwordx4 v248, s[100:101]
	ds_read_b64_tr_b16 v[202:203], v238 offset:16384
	ds_read_b64_tr_b16 v[204:205], v238 offset:20480
	v_mfma_f32_16x16x32_bf16 v[102:105], v[186:189], v[170:173], v[102:105]
	ds_read_b128 v[186:189], v237 offset:40960
	v_add_f32_e32 v250, v141, v250
	v_cvt_pk_bf16_f32 v130, v130, v131
	s_waitcnt lgkmcnt(5)
	v_mfma_f32_16x16x32_bf16 v[106:109], v[190:193], v[154:157], v[106:109]
	v_cvt_pk_bf16_f32 v131, v132, v133
	ds_read_b64_tr_b16 v[206:207], v239 offset:16384
	ds_read_b64_tr_b16 v[208:209], v239 offset:20480
	v_mfma_f32_16x16x32_bf16 v[110:113], v[190:193], v[170:173], v[110:113]
	ds_read_b128 v[190:193], v237 offset:45056
	v_cvt_pk_bf16_f32 v132, v138, v139
	v_cvt_pk_bf16_f32 v133, v140, v141
	s_waitcnt lgkmcnt(7)
	v_mfma_f32_16x16x32_bf16 v[82:85], v[178:181], v[158:161], v[82:85]
	v_add_f32_e32 v251, v134, v251
	ds_read_b64_tr_b16 v[210:211], v240 offset:16384
	ds_read_b64_tr_b16 v[212:213], v240 offset:20480
	v_mfma_f32_16x16x32_bf16 v[86:89], v[178:181], v[174:177], v[86:89]
	v_add_f32_e32 v251, v135, v251
	v_add_f32_e32 v251, v136, v251
	s_waitcnt lgkmcnt(8)
	v_mfma_f32_16x16x32_bf16 v[90:93], v[182:185], v[158:161], v[90:93]
	v_add_f32_e32 v251, v137, v251
	ds_read_b64_tr_b16 v[214:215], v241 offset:16384
	ds_read_b64_tr_b16 v[216:217], v241 offset:20480
	v_mfma_f32_16x16x32_bf16 v[94:97], v[182:185], v[174:177], v[94:97]
	v_add_f32_e32 v251, v142, v251
	v_add_f32_e32 v251, v143, v251
	s_waitcnt lgkmcnt(7)
	v_mfma_f32_16x16x32_bf16 v[98:101], v[186:189], v[158:161], v[98:101]
	v_add_f32_e32 v251, v144, v251
	s_add_u32 m0, s80, 1024
	s_nop 0
	global_load_lds_dwordx4 v249, s[100:101]
	ds_read_b64_tr_b16 v[218:219], v242 offset:16384
	ds_read_b64_tr_b16 v[220:221], v242 offset:20480
	v_mfma_f32_16x16x32_bf16 v[102:105], v[186:189], v[174:177], v[102:105]
	v_add_f32_e32 v251, v145, v251
	v_cvt_pk_bf16_f32 v134, v134, v135
	s_waitcnt lgkmcnt(6)
; #define SBAR() __builtin_amdgcn_sched_barrier(0)
; __device__ __forceinline__ void partialSM(f32x16& p0, f32x16& p1, float mC) {
;   (void)mC; (void)p1;
;   for (int r = 0; r < 16; ++r) p0[r] = __builtin_amdgcn_exp2f(p0[r]);
; }
; template <int OFF> __device__ __forceinline__ s16x4 tr_read(int vb) {
;   s16x4 r; asm volatile("ds_read_b64_tr_b16 %0, %1 offset:%2" : "=&v"(r) : "v"(vb), "i"(OFF) : "memory"); return r;
; }
; template <int D0> __device__ __forceinline__ void pv_one(f32x16& od, int vb, bf16x8 pa0, bf16x8 pa1, bf16x8 pa2, bf16x8 pa3) {
;   const s16x4 l0 = tr_read<v_rd_off(D0, 0, 0)>(vb), h0 = tr_read<v_rd_off(D0, 0, 1)>(vb), l1 = tr_read<v_rd_off(D0, 1, 0)>(vb), h1 = tr_read<v_rd_off(D0, 1, 1)>(vb);
;   const s16x4 l2 = tr_read<v_rd_off(D0, 2, 0)>(vb), h2 = tr_read<v_rd_off(D0, 2, 1)>(vb), l3 = tr_read<v_rd_off(D0, 3, 0)>(vb), h3 = tr_read<v_rd_off(D0, 3, 1)>(vb);
;   asm volatile("s_waitcnt lgkmcnt(0)" ::: "memory"); SBAR();
;     ...
;   od = __builtin_amdgcn_mfma_f32_32x32x16_bf16(pa0, PK(l0, h0), od, 0, 0, 0);
;   od = __builtin_amdgcn_mfma_f32_32x32x16_bf16(pa1, PK(l1, h1), od, 0, 0, 0);
;   od = __builtin_amdgcn_mfma_f32_32x32x16_bf16(pa2, PK(l2, h2), od, 0, 0, 0);
;   od = __builtin_amdgcn_mfma_f32_32x32x16_bf16(pa3, PK(l3, h3), od, 0, 0, 0);
;     ...
; }
; __device__ __forceinline__ void pv_d0(f32x16* o, int vb, bf16x8 pa0, bf16x8 pa1, bf16x8 pa2, bf16x8 pa3) {
;   pv_one<0>(o[0], vb, pa0, pa1, pa2, pa3); pv_one<1>(o[1], vb, pa0, pa1, pa2, pa3); pv_one<2>(o[2], vb, pa0, pa1, pa2, pa3); pv_one<3>(o[3], vb, pa0, pa1, pa2, pa3);
	v_mfma_f32_16x16x32_bf16 v[106:109], v[190:193], v[158:161], v[106:109]
	v_cvt_pk_bf16_f32 v135, v136, v137
	ds_read_b64_tr_b16 v[222:223], v243 offset:16384
	ds_read_b64_tr_b16 v[224:225], v243 offset:20480
	v_mfma_f32_16x16x32_bf16 v[110:113], v[190:193], v[174:177], v[110:113]
	v_cvt_pk_bf16_f32 v136, v142, v143
	v_cvt_pk_bf16_f32 v137, v144, v145
	v_mfma_f32_16x16x32_bf16 v[18:21], v[202:205], v[114:117], v[18:21]
	v_exp_f32_e32 v82, v82
	v_mfma_f32_16x16x32_bf16 v[22:25], v[202:205], v[118:121], v[22:25]
	ds_read_b64_tr_b16 v[202:203], v244 offset:16384
	ds_read_b64_tr_b16 v[204:205], v244 offset:20480
	v_exp_f32_e32 v83, v83
	v_mfma_f32_16x16x32_bf16 v[26:29], v[206:209], v[114:117], v[26:29]
	v_exp_f32_e32 v84, v84
	v_mfma_f32_16x16x32_bf16 v[30:33], v[206:209], v[118:121], v[30:33]
	ds_read_b64_tr_b16 v[206:207], v245 offset:16384
	ds_read_b64_tr_b16 v[208:209], v245 offset:20480
	v_exp_f32_e32 v85, v85
	s_waitcnt lgkmcnt(10)
	v_mfma_f32_16x16x32_bf16 v[34:37], v[210:213], v[114:117], v[34:37]
	v_exp_f32_e32 v86, v86
	v_mfma_f32_16x16x32_bf16 v[38:41], v[210:213], v[118:121], v[38:41]
	ds_read_b64_tr_b16 v[210:211], v238 offset:24576
	ds_read_b64_tr_b16 v[212:213], v238 offset:28672
	v_exp_f32_e32 v87, v87
	s_waitcnt lgkmcnt(10)
	v_mfma_f32_16x16x32_bf16 v[42:45], v[214:217], v[114:117], v[42:45]
	v_exp_f32_e32 v88, v88
	v_mfma_f32_16x16x32_bf16 v[46:49], v[214:217], v[118:121], v[46:49]
	ds_read_b64_tr_b16 v[214:215], v239 offset:24576
	ds_read_b64_tr_b16 v[216:217], v239 offset:28672
	v_exp_f32_e32 v89, v89
	s_waitcnt lgkmcnt(10)
	v_mfma_f32_16x16x32_bf16 v[50:53], v[218:221], v[114:117], v[50:53]
	v_exp_f32_e32 v90, v90
	v_mfma_f32_16x16x32_bf16 v[54:57], v[218:221], v[118:121], v[54:57]
	ds_read_b64_tr_b16 v[218:219], v240 offset:24576
	ds_read_b64_tr_b16 v[220:221], v240 offset:28672
	v_exp_f32_e32 v91, v91
	s_waitcnt lgkmcnt(10)
	v_mfma_f32_16x16x32_bf16 v[58:61], v[222:225], v[114:117], v[58:61]
	v_exp_f32_e32 v92, v92
	v_mfma_f32_16x16x32_bf16 v[62:65], v[222:225], v[118:121], v[62:65]
	ds_read_b64_tr_b16 v[222:223], v241 offset:24576
	ds_read_b64_tr_b16 v[224:225], v241 offset:28672
	v_exp_f32_e32 v93, v93
	s_waitcnt lgkmcnt(10)
	v_mfma_f32_16x16x32_bf16 v[66:69], v[202:205], v[114:117], v[66:69]
	v_exp_f32_e32 v94, v94
	v_mfma_f32_16x16x32_bf16 v[70:73], v[202:205], v[118:121], v[70:73]
	ds_read_b64_tr_b16 v[202:203], v242 offset:24576
	ds_read_b64_tr_b16 v[204:205], v242 offset:28672
	v_exp_f32_e32 v95, v95
	s_waitcnt lgkmcnt(10)
	v_mfma_f32_16x16x32_bf16 v[74:77], v[206:209], v[114:117], v[74:77]
	v_exp_f32_e32 v96, v96
	v_mfma_f32_16x16x32_bf16 v[78:81], v[206:209], v[118:121], v[78:81]
	ds_read_b64_tr_b16 v[206:207], v243 offset:24576
	ds_read_b64_tr_b16 v[208:209], v243 offset:28672
	v_exp_f32_e32 v97, v97
	s_waitcnt lgkmcnt(10)
	v_mfma_f32_16x16x32_bf16 v[18:21], v[210:213], v[130:133], v[18:21]
	v_exp_f32_e32 v98, v98
	v_mfma_f32_16x16x32_bf16 v[22:25], v[210:213], v[134:137], v[22:25]
	ds_read_b64_tr_b16 v[210:211], v244 offset:24576
	ds_read_b64_tr_b16 v[212:213], v244 offset:28672
	v_exp_f32_e32 v99, v99
	s_waitcnt lgkmcnt(10)
	v_mfma_f32_16x16x32_bf16 v[26:29], v[214:217], v[130:133], v[26:29]
	v_exp_f32_e32 v100, v100
	v_mfma_f32_16x16x32_bf16 v[30:33], v[214:217], v[134:137], v[30:33]
	ds_read_b64_tr_b16 v[214:215], v245 offset:24576
	ds_read_b64_tr_b16 v[216:217], v245 offset:28672
	v_exp_f32_e32 v101, v101
	s_waitcnt lgkmcnt(10)
	v_mfma_f32_16x16x32_bf16 v[34:37], v[218:221], v[130:133], v[34:37]
	v_exp_f32_e32 v102, v102
	v_mfma_f32_16x16x32_bf16 v[38:41], v[218:221], v[134:137], v[38:41]
	v_exp_f32_e32 v103, v103
	s_waitcnt lgkmcnt(8)
	v_mfma_f32_16x16x32_bf16 v[42:45], v[222:225], v[130:133], v[42:45]
	v_exp_f32_e32 v104, v104
	v_mfma_f32_16x16x32_bf16 v[46:49], v[222:225], v[134:137], v[46:49]
	v_exp_f32_e32 v105, v105
	s_waitcnt lgkmcnt(6)
	v_mfma_f32_16x16x32_bf16 v[50:53], v[202:205], v[130:133], v[50:53]
	v_exp_f32_e32 v106, v106
	ds_read_b128 v[178:181], v234 offset:49152
	v_mfma_f32_16x16x32_bf16 v[54:57], v[202:205], v[134:137], v[54:57]
	v_exp_f32_e32 v107, v107
	s_waitcnt lgkmcnt(5)
	v_mfma_f32_16x16x32_bf16 v[58:61], v[206:209], v[130:133], v[58:61]
	v_exp_f32_e32 v108, v108
	ds_read_b128 v[182:185], v234 offset:53248
	v_mfma_f32_16x16x32_bf16 v[62:65], v[206:209], v[134:137], v[62:65]
	v_exp_f32_e32 v109, v109
	s_waitcnt lgkmcnt(4)
	v_mfma_f32_16x16x32_bf16 v[66:69], v[210:213], v[130:133], v[66:69]
	v_exp_f32_e32 v110, v110
	ds_read_b128 v[186:189], v234 offset:57344
	v_mfma_f32_16x16x32_bf16 v[70:73], v[210:213], v[134:137], v[70:73]
	v_exp_f32_e32 v111, v111
	s_waitcnt lgkmcnt(3)
	v_mfma_f32_16x16x32_bf16 v[74:77], v[214:217], v[130:133], v[74:77]
	v_exp_f32_e32 v112, v112
	ds_read_b128 v[190:193], v234 offset:61440
	v_mfma_f32_16x16x32_bf16 v[78:81], v[214:217], v[134:137], v[78:81]
	v_exp_f32_e32 v113, v113
	s_waitcnt vmcnt(4)
	s_barrier
; #define SBAR() __builtin_amdgcn_sched_barrier(0)
; #define SLOAD(i, k0) do { sr_[i].vs0 = St::ld8(&Vh[(long)((k0) + sr) * LDK + sc]); sr_[i].vs1 = St::ld8(&Vh[(long)((k0) + 32 + sr) * LDK + sc]); \
;     sr_[i].ks0 = St::ld8(&Kh[(long)((k0) + sr) * LDK + sc]); sr_[i].ks1 = St::ld8(&Kh[(long)((k0) + 32 + sr) * LDK + sc]); } while (0)
; __device__ __forceinline__ void finishSM(f32x16& p0, f32x16& p1, float& l_reg, bf16x8& pa0, bf16x8& pa1, bf16x8& pa2, bf16x8& pa3) {
;   for (int r = 0; r < 16; ++r) p1[r] = __builtin_amdgcn_exp2f(p1[r]);
;   float ps = 0; for (int r = 0; r < 16; ++r) ps += p0[r]; for (int r = 0; r < 16; ++r) ps += p1[r];
;   { auto rr = __builtin_amdgcn_permlane32_swap(__float_as_uint(ps), __float_as_uint(ps), false, false);
;     ps = __uint_as_float(rr[0]) + __uint_as_float(rr[1]); }
;   l_reg += ps;
;     ...
;   PK4(p0, 0, pa0); PK4(p0, 8, pa1); PK4(p1, 0, pa2); PK4(p1, 8, pa3);
;     ...
; }
; __device__ __forceinline__ void qkt(f32x16& p0, f32x16& p1, const bf16* Ks, const bf16x8* qr, int r32, int hi, const f32x16& negm) {
; #pragma unroll
;   for (int d0 = 0; d0 < 8; ++d0) { int cb = (d0 * 16 + hi * 8) * 2;
;     bf16x8 b0 = *reinterpret_cast<const bf16x8*>((const char*)Ks + KSWZ(r32, cb));
;     bf16x8 b1 = *reinterpret_cast<const bf16x8*>((const char*)Ks + KSWZ(32 + r32, cb));
;     if (d0 == 0) { p0 = __builtin_amdgcn_mfma_f32_32x32x16_bf16(b0, qr[0], negm, 0, 0, 0); p1 = __builtin_amdgcn_mfma_f32_32x32x16_bf16(b1, qr[0], negm, 0, 0, 0); }
;     else { p0 = __builtin_amdgcn_mfma_f32_32x32x16_bf16(b0, qr[d0], p0, 0, 0, 0); p1 = __builtin_amdgcn_mfma_f32_32x32x16_bf16(b1, qr[d0], p1, 0, 0, 0); } }
; }
; template <typename TQ> ...
;     ...
;   for (int j = 1; j + 1 < NT; j += 2) {
;     SBAR(); SLOAD(SO, (j + SDEPTH) * KVBLK); SBAR();
;     qkt(pB0, pB1, (bf16*)((char*)K_lds + SHM_K), qr, r32, hi, negm);
;     finishSM(pA0, pA1, l_reg, pa0, pa1, pa2, pa3); SBAR();
;     pv_d0(o, vb0, pa0, pa1, pa2, pa3); partialSM(pB0, pB1, mC);
	s_waitcnt lgkmcnt(3)
	v_mfma_f32_16x16x32_bf16 v[114:117], v[178:181], v[146:149], v[2:5]
	v_add_f32_e32 v250, v82, v250
	s_add_u32 s98, s98, 0x8000
	s_addc_u32 s99, s99, 0
	s_add_u32 s100, s100, 0x8000
	s_addc_u32 s101, s101, 0
	v_mfma_f32_16x16x32_bf16 v[118:121], v[178:181], v[162:165], v[2:5]
	ds_read_b128 v[178:181], v235 offset:49152
	v_add_f32_e32 v250, v83, v250
	v_add_f32_e32 v250, v84, v250
	s_waitcnt lgkmcnt(3)
	v_mfma_f32_16x16x32_bf16 v[122:125], v[182:185], v[146:149], v[2:5]
	v_add_f32_e32 v250, v85, v250
	v_mfma_f32_16x16x32_bf16 v[126:129], v[182:185], v[162:165], v[2:5]
	ds_read_b128 v[182:185], v235 offset:53248
	v_add_f32_e32 v250, v90, v250
	v_add_f32_e32 v250, v91, v250
	s_waitcnt lgkmcnt(3)
	v_mfma_f32_16x16x32_bf16 v[130:133], v[186:189], v[146:149], v[2:5]
	v_add_f32_e32 v250, v92, v250
	s_add_u32 m0, s79, 32768
	s_nop 0
	global_load_lds_dwordx4 v246, s[98:99]
	v_mfma_f32_16x16x32_bf16 v[134:137], v[186:189], v[162:165], v[2:5]
	ds_read_b128 v[186:189], v235 offset:57344
	v_add_f32_e32 v250, v93, v250
	v_cvt_pk_bf16_f32 v82, v82, v83
	s_waitcnt lgkmcnt(3)
	v_mfma_f32_16x16x32_bf16 v[138:141], v[190:193], v[146:149], v[2:5]
	v_cvt_pk_bf16_f32 v83, v84, v85
	v_mfma_f32_16x16x32_bf16 v[142:145], v[190:193], v[162:165], v[2:5]
	ds_read_b128 v[190:193], v235 offset:61440
	v_cvt_pk_bf16_f32 v84, v90, v91
	v_cvt_pk_bf16_f32 v85, v92, v93
	s_waitcnt lgkmcnt(3)
	v_mfma_f32_16x16x32_bf16 v[114:117], v[178:181], v[150:153], v[114:117]
	v_add_f32_e32 v251, v86, v251
	v_mfma_f32_16x16x32_bf16 v[118:121], v[178:181], v[166:169], v[118:121]
	ds_read_b128 v[178:181], v236 offset:49152
	v_add_f32_e32 v251, v87, v251
	v_add_f32_e32 v251, v88, v251
	s_waitcnt lgkmcnt(3)
	v_mfma_f32_16x16x32_bf16 v[122:125], v[182:185], v[150:153], v[122:125]
	v_add_f32_e32 v251, v89, v251
	v_mfma_f32_16x16x32_bf16 v[126:129], v[182:185], v[166:169], v[126:129]
	ds_read_b128 v[182:185], v236 offset:53248
	v_add_f32_e32 v251, v94, v251
	v_add_f32_e32 v251, v95, v251
	s_waitcnt lgkmcnt(3)
	v_mfma_f32_16x16x32_bf16 v[130:133], v[186:189], v[150:153], v[130:133]
	v_add_f32_e32 v251, v96, v251
	s_add_u32 m0, s79, 33792
	s_nop 0
	global_load_lds_dwordx4 v247, s[98:99]
	v_mfma_f32_16x16x32_bf16 v[134:137], v[186:189], v[166:169], v[134:137]
	ds_read_b128 v[186:189], v236 offset:57344
	v_add_f32_e32 v251, v97, v251
	v_cvt_pk_bf16_f32 v86, v86, v87
	s_waitcnt lgkmcnt(3)
	v_mfma_f32_16x16x32_bf16 v[138:141], v[190:193], v[150:153], v[138:141]
	v_cvt_pk_bf16_f32 v87, v88, v89
	v_mfma_f32_16x16x32_bf16 v[142:145], v[190:193], v[166:169], v[142:145]
	ds_read_b128 v[190:193], v236 offset:61440
	v_cvt_pk_bf16_f32 v88, v94, v95
	v_cvt_pk_bf16_f32 v89, v96, v97
	s_waitcnt lgkmcnt(3)
	v_mfma_f32_16x16x32_bf16 v[114:117], v[178:181], v[154:157], v[114:117]
	v_add_f32_e32 v250, v98, v250
	v_mfma_f32_16x16x32_bf16 v[118:121], v[178:181], v[170:173], v[118:121]
	ds_read_b128 v[178:181], v237 offset:49152
	v_add_f32_e32 v250, v99, v250
	v_add_f32_e32 v250, v100, v250
	s_waitcnt lgkmcnt(3)
	v_mfma_f32_16x16x32_bf16 v[122:125], v[182:185], v[154:157], v[122:125]
	v_add_f32_e32 v250, v101, v250
	v_mfma_f32_16x16x32_bf16 v[126:129], v[182:185], v[170:173], v[126:129]
	ds_read_b128 v[182:185], v237 offset:53248
	v_add_f32_e32 v250, v106, v250
	v_add_f32_e32 v250, v107, v250
	s_waitcnt lgkmcnt(3)
	v_mfma_f32_16x16x32_bf16 v[130:133], v[186:189], v[154:157], v[130:133]
	v_add_f32_e32 v250, v108, v250
	s_add_u32 m0, s80, 16384
	s_nop 0
	global_load_lds_dwordx4 v248, s[100:101]
	ds_read_b64_tr_b16 v[202:203], v238 offset:32768
	ds_read_b64_tr_b16 v[204:205], v238 offset:36864
	v_mfma_f32_16x16x32_bf16 v[134:137], v[186:189], v[170:173], v[134:137]
	ds_read_b128 v[186:189], v237 offset:57344
	v_add_f32_e32 v250, v109, v250
	v_cvt_pk_bf16_f32 v98, v98, v99
	s_waitcnt lgkmcnt(5)
	v_mfma_f32_16x16x32_bf16 v[138:141], v[190:193], v[154:157], v[138:141]
	v_cvt_pk_bf16_f32 v99, v100, v101
	ds_read_b64_tr_b16 v[206:207], v239 offset:32768
	ds_read_b64_tr_b16 v[208:209], v239 offset:36864
	v_mfma_f32_16x16x32_bf16 v[142:145], v[190:193], v[170:173], v[142:145]
	ds_read_b128 v[190:193], v237 offset:61440
	v_cvt_pk_bf16_f32 v100, v106, v107
	v_cvt_pk_bf16_f32 v101, v108, v109
	s_waitcnt lgkmcnt(7)
	v_mfma_f32_16x16x32_bf16 v[114:117], v[178:181], v[158:161], v[114:117]
	v_add_f32_e32 v251, v102, v251
	ds_read_b64_tr_b16 v[210:211], v240 offset:32768
	ds_read_b64_tr_b16 v[212:213], v240 offset:36864
	v_mfma_f32_16x16x32_bf16 v[118:121], v[178:181], v[174:177], v[118:121]
	v_add_f32_e32 v251, v103, v251
	v_add_f32_e32 v251, v104, v251
	s_waitcnt lgkmcnt(8)
	v_mfma_f32_16x16x32_bf16 v[122:125], v[182:185], v[158:161], v[122:125]
	v_add_f32_e32 v251, v105, v251
	ds_read_b64_tr_b16 v[214:215], v241 offset:32768
	ds_read_b64_tr_b16 v[216:217], v241 offset:36864
	v_mfma_f32_16x16x32_bf16 v[126:129], v[182:185], v[174:177], v[126:129]
	v_add_f32_e32 v251, v110, v251
	v_add_f32_e32 v251, v111, v251
	s_waitcnt lgkmcnt(7)
	v_mfma_f32_16x16x32_bf16 v[130:133], v[186:189], v[158:161], v[130:133]
	v_add_f32_e32 v251, v112, v251
	s_add_u32 m0, s80, 17408
	s_nop 0
	global_load_lds_dwordx4 v249, s[100:101]
	ds_read_b64_tr_b16 v[218:219], v242 offset:32768
	ds_read_b64_tr_b16 v[220:221], v242 offset:36864
	v_mfma_f32_16x16x32_bf16 v[134:137], v[186:189], v[174:177], v[134:137]
	v_add_f32_e32 v251, v113, v251
	v_cvt_pk_bf16_f32 v102, v102, v103
	s_waitcnt lgkmcnt(6)
; #define SBAR() __builtin_amdgcn_sched_barrier(0)
; __device__ __forceinline__ void partialSM(f32x16& p0, f32x16& p1, float mC) {
;   (void)mC; (void)p1;
;   for (int r = 0; r < 16; ++r) p0[r] = __builtin_amdgcn_exp2f(p0[r]);
; }
; template <int OFF> __device__ __forceinline__ s16x4 tr_read(int vb) {
;   s16x4 r; asm volatile("ds_read_b64_tr_b16 %0, %1 offset:%2" : "=&v"(r) : "v"(vb), "i"(OFF) : "memory"); return r;
; }
; template <int D0> __device__ __forceinline__ void pv_one(f32x16& od, int vb, bf16x8 pa0, bf16x8 pa1, bf16x8 pa2, bf16x8 pa3) {
;   const s16x4 l0 = tr_read<v_rd_off(D0, 0, 0)>(vb), h0 = tr_read<v_rd_off(D0, 0, 1)>(vb), l1 = tr_read<v_rd_off(D0, 1, 0)>(vb), h1 = tr_read<v_rd_off(D0, 1, 1)>(vb);
;   const s16x4 l2 = tr_read<v_rd_off(D0, 2, 0)>(vb), h2 = tr_read<v_rd_off(D0, 2, 1)>(vb), l3 = tr_read<v_rd_off(D0, 3, 0)>(vb), h3 = tr_read<v_rd_off(D0, 3, 1)>(vb);
;   asm volatile("s_waitcnt lgkmcnt(0)" ::: "memory"); SBAR();
;     ...
;   od = __builtin_amdgcn_mfma_f32_32x32x16_bf16(pa0, PK(l0, h0), od, 0, 0, 0);
;   od = __builtin_amdgcn_mfma_f32_32x32x16_bf16(pa1, PK(l1, h1), od, 0, 0, 0);
;   od = __builtin_amdgcn_mfma_f32_32x32x16_bf16(pa2, PK(l2, h2), od, 0, 0, 0);
;   od = __builtin_amdgcn_mfma_f32_32x32x16_bf16(pa3, PK(l3, h3), od, 0, 0, 0);
;     ...
; }
; __device__ __forceinline__ void pv_d0(f32x16* o, int vb, bf16x8 pa0, bf16x8 pa1, bf16x8 pa2, bf16x8 pa3) {
;   pv_one<0>(o[0], vb, pa0, pa1, pa2, pa3); pv_one<1>(o[1], vb, pa0, pa1, pa2, pa3); pv_one<2>(o[2], vb, pa0, pa1, pa2, pa3); pv_one<3>(o[3], vb, pa0, pa1, pa2, pa3);
	v_mfma_f32_16x16x32_bf16 v[138:141], v[190:193], v[158:161], v[138:141]
	v_cvt_pk_bf16_f32 v103, v104, v105
	ds_read_b64_tr_b16 v[222:223], v243 offset:32768
	ds_read_b64_tr_b16 v[224:225], v243 offset:36864
	v_mfma_f32_16x16x32_bf16 v[142:145], v[190:193], v[174:177], v[142:145]
	v_cvt_pk_bf16_f32 v104, v110, v111
	v_cvt_pk_bf16_f32 v105, v112, v113
	v_mfma_f32_16x16x32_bf16 v[18:21], v[202:205], v[82:85], v[18:21]
	v_exp_f32_e32 v114, v114
	v_mfma_f32_16x16x32_bf16 v[22:25], v[202:205], v[86:89], v[22:25]
	ds_read_b64_tr_b16 v[202:203], v244 offset:32768
	ds_read_b64_tr_b16 v[204:205], v244 offset:36864
	v_exp_f32_e32 v115, v115
	v_mfma_f32_16x16x32_bf16 v[26:29], v[206:209], v[82:85], v[26:29]
	v_exp_f32_e32 v116, v116
	v_mfma_f32_16x16x32_bf16 v[30:33], v[206:209], v[86:89], v[30:33]
	ds_read_b64_tr_b16 v[206:207], v245 offset:32768
	ds_read_b64_tr_b16 v[208:209], v245 offset:36864
	v_exp_f32_e32 v117, v117
	s_waitcnt lgkmcnt(10)
	v_mfma_f32_16x16x32_bf16 v[34:37], v[210:213], v[82:85], v[34:37]
	v_exp_f32_e32 v118, v118
	v_mfma_f32_16x16x32_bf16 v[38:41], v[210:213], v[86:89], v[38:41]
	ds_read_b64_tr_b16 v[210:211], v238 offset:40960
	ds_read_b64_tr_b16 v[212:213], v238 offset:45056
	v_exp_f32_e32 v119, v119
	s_waitcnt lgkmcnt(10)
	v_mfma_f32_16x16x32_bf16 v[42:45], v[214:217], v[82:85], v[42:45]
	v_exp_f32_e32 v120, v120
	v_mfma_f32_16x16x32_bf16 v[46:49], v[214:217], v[86:89], v[46:49]
	ds_read_b64_tr_b16 v[214:215], v239 offset:40960
	ds_read_b64_tr_b16 v[216:217], v239 offset:45056
	v_exp_f32_e32 v121, v121
	s_waitcnt lgkmcnt(10)
	v_mfma_f32_16x16x32_bf16 v[50:53], v[218:221], v[82:85], v[50:53]
	v_exp_f32_e32 v122, v122
	v_mfma_f32_16x16x32_bf16 v[54:57], v[218:221], v[86:89], v[54:57]
	ds_read_b64_tr_b16 v[218:219], v240 offset:40960
	ds_read_b64_tr_b16 v[220:221], v240 offset:45056
	v_exp_f32_e32 v123, v123
	s_waitcnt lgkmcnt(10)
	v_mfma_f32_16x16x32_bf16 v[58:61], v[222:225], v[82:85], v[58:61]
	v_exp_f32_e32 v124, v124
	v_mfma_f32_16x16x32_bf16 v[62:65], v[222:225], v[86:89], v[62:65]
	ds_read_b64_tr_b16 v[222:223], v241 offset:40960
	ds_read_b64_tr_b16 v[224:225], v241 offset:45056
	v_exp_f32_e32 v125, v125
	s_waitcnt lgkmcnt(10)
	v_mfma_f32_16x16x32_bf16 v[66:69], v[202:205], v[82:85], v[66:69]
	v_exp_f32_e32 v126, v126
	v_mfma_f32_16x16x32_bf16 v[70:73], v[202:205], v[86:89], v[70:73]
	ds_read_b64_tr_b16 v[202:203], v242 offset:40960
	ds_read_b64_tr_b16 v[204:205], v242 offset:45056
	v_exp_f32_e32 v127, v127
	s_waitcnt lgkmcnt(10)
	v_mfma_f32_16x16x32_bf16 v[74:77], v[206:209], v[82:85], v[74:77]
	v_exp_f32_e32 v128, v128
	v_mfma_f32_16x16x32_bf16 v[78:81], v[206:209], v[86:89], v[78:81]
	ds_read_b64_tr_b16 v[206:207], v243 offset:40960
	ds_read_b64_tr_b16 v[208:209], v243 offset:45056
	v_exp_f32_e32 v129, v129
	s_waitcnt lgkmcnt(10)
	v_mfma_f32_16x16x32_bf16 v[18:21], v[210:213], v[98:101], v[18:21]
	v_exp_f32_e32 v130, v130
	v_mfma_f32_16x16x32_bf16 v[22:25], v[210:213], v[102:105], v[22:25]
	ds_read_b64_tr_b16 v[210:211], v244 offset:40960
	ds_read_b64_tr_b16 v[212:213], v244 offset:45056
	v_exp_f32_e32 v131, v131
	s_waitcnt lgkmcnt(10)
	v_mfma_f32_16x16x32_bf16 v[26:29], v[214:217], v[98:101], v[26:29]
	v_exp_f32_e32 v132, v132
	v_mfma_f32_16x16x32_bf16 v[30:33], v[214:217], v[102:105], v[30:33]
	ds_read_b64_tr_b16 v[214:215], v245 offset:40960
	ds_read_b64_tr_b16 v[216:217], v245 offset:45056
	v_exp_f32_e32 v133, v133
	s_waitcnt lgkmcnt(10)
	v_mfma_f32_16x16x32_bf16 v[34:37], v[218:221], v[98:101], v[34:37]
	v_exp_f32_e32 v134, v134
	v_mfma_f32_16x16x32_bf16 v[38:41], v[218:221], v[102:105], v[38:41]
	v_exp_f32_e32 v135, v135
	s_waitcnt lgkmcnt(8)
	v_mfma_f32_16x16x32_bf16 v[42:45], v[222:225], v[98:101], v[42:45]
	v_exp_f32_e32 v136, v136
	v_mfma_f32_16x16x32_bf16 v[46:49], v[222:225], v[102:105], v[46:49]
	v_exp_f32_e32 v137, v137
	s_waitcnt lgkmcnt(6)
	v_mfma_f32_16x16x32_bf16 v[50:53], v[202:205], v[98:101], v[50:53]
	v_exp_f32_e32 v138, v138
	ds_read_b128 v[178:181], v234 offset:0
	v_mfma_f32_16x16x32_bf16 v[54:57], v[202:205], v[102:105], v[54:57]
	v_exp_f32_e32 v139, v139
	s_waitcnt lgkmcnt(5)
	v_mfma_f32_16x16x32_bf16 v[58:61], v[206:209], v[98:101], v[58:61]
	v_exp_f32_e32 v140, v140
	ds_read_b128 v[182:185], v234 offset:4096
	v_mfma_f32_16x16x32_bf16 v[62:65], v[206:209], v[102:105], v[62:65]
	v_exp_f32_e32 v141, v141
	s_waitcnt lgkmcnt(4)
	v_mfma_f32_16x16x32_bf16 v[66:69], v[210:213], v[98:101], v[66:69]
	v_exp_f32_e32 v142, v142
	ds_read_b128 v[186:189], v234 offset:8192
	v_mfma_f32_16x16x32_bf16 v[70:73], v[210:213], v[102:105], v[70:73]
	v_exp_f32_e32 v143, v143
	s_waitcnt lgkmcnt(3)
	v_mfma_f32_16x16x32_bf16 v[74:77], v[214:217], v[98:101], v[74:77]
	v_exp_f32_e32 v144, v144
	ds_read_b128 v[190:193], v234 offset:12288
	v_mfma_f32_16x16x32_bf16 v[78:81], v[214:217], v[102:105], v[78:81]
	v_exp_f32_e32 v145, v145
	s_waitcnt vmcnt(4)
	s_barrier
; __device__ __forceinline__ void finishSM(f32x16& p0, f32x16& p1, float& l_reg, bf16x8& pa0, bf16x8& pa1, bf16x8& pa2, bf16x8& pa3) {
;   for (int r = 0; r < 16; ++r) p1[r] = __builtin_amdgcn_exp2f(p1[r]);
;   float ps = 0; for (int r = 0; r < 16; ++r) ps += p0[r]; for (int r = 0; r < 16; ++r) ps += p1[r];
;   { auto rr = __builtin_amdgcn_permlane32_swap(__float_as_uint(ps), __float_as_uint(ps), false, false);
;     ps = __uint_as_float(rr[0]) + __uint_as_float(rr[1]); }
;   l_reg += ps;
;     ...
;   PK4(p0, 0, pa0); PK4(p0, 8, pa1); PK4(p1, 0, pa2); PK4(p1, 8, pa3);
;     ...
; }
; __device__ __forceinline__ void qkt(f32x16& p0, f32x16& p1, const bf16* Ks, const bf16x8* qr, int r32, int hi, const f32x16& negm) {
; #pragma unroll
;   for (int d0 = 0; d0 < 8; ++d0) { int cb = (d0 * 16 + hi * 8) * 2;
;     bf16x8 b0 = *reinterpret_cast<const bf16x8*>((const char*)Ks + KSWZ(r32, cb));
;     bf16x8 b1 = *reinterpret_cast<const bf16x8*>((const char*)Ks + KSWZ(32 + r32, cb));
;     if (d0 == 0) { p0 = __builtin_amdgcn_mfma_f32_32x32x16_bf16(b0, qr[0], negm, 0, 0, 0); p1 = __builtin_amdgcn_mfma_f32_32x32x16_bf16(b1, qr[0], negm, 0, 0, 0); }
;     else { p0 = __builtin_amdgcn_mfma_f32_32x32x16_bf16(b0, qr[d0], p0, 0, 0, 0); p1 = __builtin_amdgcn_mfma_f32_32x32x16_bf16(b1, qr[d0], p1, 0, 0, 0); } }
; }
	s_waitcnt lgkmcnt(3)
	v_mfma_f32_16x16x32_bf16 v[82:85], v[178:181], v[146:149], v[2:5]
	v_add_f32_e32 v250, v114, v250
	s_add_u32 s98, s98, 0x8000
	s_addc_u32 s99, s99, 0
	s_add_u32 s100, s100, 0x8000
	s_addc_u32 s101, s101, 0
	v_mfma_f32_16x16x32_bf16 v[86:89], v[178:181], v[162:165], v[2:5]
	ds_read_b128 v[178:181], v235 offset:0
	v_add_f32_e32 v250, v115, v250
	v_add_f32_e32 v250, v116, v250
	s_waitcnt lgkmcnt(3)
	v_mfma_f32_16x16x32_bf16 v[90:93], v[182:185], v[146:149], v[2:5]
	v_add_f32_e32 v250, v117, v250
	v_mfma_f32_16x16x32_bf16 v[94:97], v[182:185], v[162:165], v[2:5]
	ds_read_b128 v[182:185], v235 offset:4096
	v_add_f32_e32 v250, v122, v250
	v_add_f32_e32 v250, v123, v250
	s_waitcnt lgkmcnt(3)
	v_mfma_f32_16x16x32_bf16 v[98:101], v[186:189], v[146:149], v[2:5]
	v_add_f32_e32 v250, v124, v250
	s_add_u32 m0, s79, 49152
	s_nop 0
	global_load_lds_dwordx4 v246, s[98:99]
	v_mfma_f32_16x16x32_bf16 v[102:105], v[186:189], v[162:165], v[2:5]
	ds_read_b128 v[186:189], v235 offset:8192
	v_add_f32_e32 v250, v125, v250
	v_cvt_pk_bf16_f32 v114, v114, v115
	s_waitcnt lgkmcnt(3)
	v_mfma_f32_16x16x32_bf16 v[106:109], v[190:193], v[146:149], v[2:5]
	v_cvt_pk_bf16_f32 v115, v116, v117
	v_mfma_f32_16x16x32_bf16 v[110:113], v[190:193], v[162:165], v[2:5]
	ds_read_b128 v[190:193], v235 offset:12288
	v_cvt_pk_bf16_f32 v116, v122, v123
	v_cvt_pk_bf16_f32 v117, v124, v125
	s_waitcnt lgkmcnt(3)
	v_mfma_f32_16x16x32_bf16 v[82:85], v[178:181], v[150:153], v[82:85]
	v_add_f32_e32 v251, v118, v251
	v_mfma_f32_16x16x32_bf16 v[86:89], v[178:181], v[166:169], v[86:89]
	ds_read_b128 v[178:181], v236 offset:0
	v_add_f32_e32 v251, v119, v251
	v_add_f32_e32 v251, v120, v251
	s_waitcnt lgkmcnt(3)
	v_mfma_f32_16x16x32_bf16 v[90:93], v[182:185], v[150:153], v[90:93]
	v_add_f32_e32 v251, v121, v251
	v_mfma_f32_16x16x32_bf16 v[94:97], v[182:185], v[166:169], v[94:97]
	ds_read_b128 v[182:185], v236 offset:4096
	v_add_f32_e32 v251, v126, v251
	v_add_f32_e32 v251, v127, v251
	s_waitcnt lgkmcnt(3)
	v_mfma_f32_16x16x32_bf16 v[98:101], v[186:189], v[150:153], v[98:101]
	v_add_f32_e32 v251, v128, v251
	s_add_u32 m0, s79, 50176
	s_nop 0
	global_load_lds_dwordx4 v247, s[98:99]
	v_mfma_f32_16x16x32_bf16 v[102:105], v[186:189], v[166:169], v[102:105]
	ds_read_b128 v[186:189], v236 offset:8192
	v_add_f32_e32 v251, v129, v251
	v_cvt_pk_bf16_f32 v118, v118, v119
	s_waitcnt lgkmcnt(3)
	v_mfma_f32_16x16x32_bf16 v[106:109], v[190:193], v[150:153], v[106:109]
	v_cvt_pk_bf16_f32 v119, v120, v121
	v_mfma_f32_16x16x32_bf16 v[110:113], v[190:193], v[166:169], v[110:113]
	ds_read_b128 v[190:193], v236 offset:12288
	v_cvt_pk_bf16_f32 v120, v126, v127
	v_cvt_pk_bf16_f32 v121, v128, v129
	s_waitcnt lgkmcnt(3)
	v_mfma_f32_16x16x32_bf16 v[82:85], v[178:181], v[154:157], v[82:85]
	v_add_f32_e32 v250, v130, v250
	v_mfma_f32_16x16x32_bf16 v[86:89], v[178:181], v[170:173], v[86:89]
	ds_read_b128 v[178:181], v237 offset:0
	v_add_f32_e32 v250, v131, v250
	v_add_f32_e32 v250, v132, v250
	s_waitcnt lgkmcnt(3)
	v_mfma_f32_16x16x32_bf16 v[90:93], v[182:185], v[154:157], v[90:93]
	v_add_f32_e32 v250, v133, v250
	v_mfma_f32_16x16x32_bf16 v[94:97], v[182:185], v[170:173], v[94:97]
	ds_read_b128 v[182:185], v237 offset:4096
	v_add_f32_e32 v250, v138, v250
	v_add_f32_e32 v250, v139, v250
	s_waitcnt lgkmcnt(3)
	v_mfma_f32_16x16x32_bf16 v[98:101], v[186:189], v[154:157], v[98:101]
	v_add_f32_e32 v250, v140, v250
	s_add_u32 m0, s80, 32768
	s_nop 0
	global_load_lds_dwordx4 v248, s[100:101]
	ds_read_b64_tr_b16 v[202:203], v238 offset:49152
	ds_read_b64_tr_b16 v[204:205], v238 offset:53248
	v_mfma_f32_16x16x32_bf16 v[102:105], v[186:189], v[170:173], v[102:105]
	ds_read_b128 v[186:189], v237 offset:8192
	v_add_f32_e32 v250, v141, v250
	v_cvt_pk_bf16_f32 v130, v130, v131
	s_waitcnt lgkmcnt(5)
	v_mfma_f32_16x16x32_bf16 v[106:109], v[190:193], v[154:157], v[106:109]
	v_cvt_pk_bf16_f32 v131, v132, v133
	ds_read_b64_tr_b16 v[206:207], v239 offset:49152
	ds_read_b64_tr_b16 v[208:209], v239 offset:53248
	v_mfma_f32_16x16x32_bf16 v[110:113], v[190:193], v[170:173], v[110:113]
	ds_read_b128 v[190:193], v237 offset:12288
	v_cvt_pk_bf16_f32 v132, v138, v139
	v_cvt_pk_bf16_f32 v133, v140, v141
	s_waitcnt lgkmcnt(7)
	v_mfma_f32_16x16x32_bf16 v[82:85], v[178:181], v[158:161], v[82:85]
	v_add_f32_e32 v251, v134, v251
	ds_read_b64_tr_b16 v[210:211], v240 offset:49152
	ds_read_b64_tr_b16 v[212:213], v240 offset:53248
	v_mfma_f32_16x16x32_bf16 v[86:89], v[178:181], v[174:177], v[86:89]
	v_add_f32_e32 v251, v135, v251
	v_add_f32_e32 v251, v136, v251
	s_waitcnt lgkmcnt(8)
	v_mfma_f32_16x16x32_bf16 v[90:93], v[182:185], v[158:161], v[90:93]
	v_add_f32_e32 v251, v137, v251
	ds_read_b64_tr_b16 v[214:215], v241 offset:49152
	ds_read_b64_tr_b16 v[216:217], v241 offset:53248
	v_mfma_f32_16x16x32_bf16 v[94:97], v[182:185], v[174:177], v[94:97]
	v_add_f32_e32 v251, v142, v251
	v_add_f32_e32 v251, v143, v251
	s_waitcnt lgkmcnt(7)
	v_mfma_f32_16x16x32_bf16 v[98:101], v[186:189], v[158:161], v[98:101]
	v_add_f32_e32 v251, v144, v251
	s_add_u32 m0, s80, 33792
	s_nop 0
	global_load_lds_dwordx4 v249, s[100:101]
	ds_read_b64_tr_b16 v[218:219], v242 offset:49152
	ds_read_b64_tr_b16 v[220:221], v242 offset:53248
	v_mfma_f32_16x16x32_bf16 v[102:105], v[186:189], v[174:177], v[102:105]
	v_add_f32_e32 v251, v145, v251
	v_cvt_pk_bf16_f32 v134, v134, v135
	s_waitcnt lgkmcnt(6)
; #define SBAR() __builtin_amdgcn_sched_barrier(0)
; __device__ __forceinline__ void partialSM(f32x16& p0, f32x16& p1, float mC) {
;   (void)mC; (void)p1;
;   for (int r = 0; r < 16; ++r) p0[r] = __builtin_amdgcn_exp2f(p0[r]);
; }
; template <int D0> __device__ __forceinline__ void pv_one(f32x16& od, int vb, bf16x8 pa0, bf16x8 pa1, bf16x8 pa2, bf16x8 pa3) {
;   const s16x4 l0 = tr_read<v_rd_off(D0, 0, 0)>(vb), h0 = tr_read<v_rd_off(D0, 0, 1)>(vb), l1 = tr_read<v_rd_off(D0, 1, 0)>(vb), h1 = tr_read<v_rd_off(D0, 1, 1)>(vb);
;   const s16x4 l2 = tr_read<v_rd_off(D0, 2, 0)>(vb), h2 = tr_read<v_rd_off(D0, 2, 1)>(vb), l3 = tr_read<v_rd_off(D0, 3, 0)>(vb), h3 = tr_read<v_rd_off(D0, 3, 1)>(vb);
;   asm volatile("s_waitcnt lgkmcnt(0)" ::: "memory"); SBAR();
;     ...
;   od = __builtin_amdgcn_mfma_f32_32x32x16_bf16(pa0, PK(l0, h0), od, 0, 0, 0);
;   od = __builtin_amdgcn_mfma_f32_32x32x16_bf16(pa1, PK(l1, h1), od, 0, 0, 0);
;   od = __builtin_amdgcn_mfma_f32_32x32x16_bf16(pa2, PK(l2, h2), od, 0, 0, 0);
;   od = __builtin_amdgcn_mfma_f32_32x32x16_bf16(pa3, PK(l3, h3), od, 0, 0, 0);
;     ...
; }
; __device__ __forceinline__ void pv_d0(f32x16* o, int vb, bf16x8 pa0, bf16x8 pa1, bf16x8 pa2, bf16x8 pa3) {
;   pv_one<0>(o[0], vb, pa0, pa1, pa2, pa3); pv_one<1>(o[1], vb, pa0, pa1, pa2, pa3); pv_one<2>(o[2], vb, pa0, pa1, pa2, pa3); pv_one<3>(o[3], vb, pa0, pa1, pa2, pa3);
	v_mfma_f32_16x16x32_bf16 v[106:109], v[190:193], v[158:161], v[106:109]
	v_cvt_pk_bf16_f32 v135, v136, v137
	ds_read_b64_tr_b16 v[222:223], v243 offset:49152
	ds_read_b64_tr_b16 v[224:225], v243 offset:53248
	v_mfma_f32_16x16x32_bf16 v[110:113], v[190:193], v[174:177], v[110:113]
	v_cvt_pk_bf16_f32 v136, v142, v143
	v_cvt_pk_bf16_f32 v137, v144, v145
	v_mfma_f32_16x16x32_bf16 v[18:21], v[202:205], v[114:117], v[18:21]
	v_exp_f32_e32 v82, v82
	v_mfma_f32_16x16x32_bf16 v[22:25], v[202:205], v[118:121], v[22:25]
	ds_read_b64_tr_b16 v[202:203], v244 offset:49152
	ds_read_b64_tr_b16 v[204:205], v244 offset:53248
	v_exp_f32_e32 v83, v83
	v_mfma_f32_16x16x32_bf16 v[26:29], v[206:209], v[114:117], v[26:29]
	v_exp_f32_e32 v84, v84
	v_mfma_f32_16x16x32_bf16 v[30:33], v[206:209], v[118:121], v[30:33]
	ds_read_b64_tr_b16 v[206:207], v245 offset:49152
	ds_read_b64_tr_b16 v[208:209], v245 offset:53248
	v_exp_f32_e32 v85, v85
	s_waitcnt lgkmcnt(10)
	v_mfma_f32_16x16x32_bf16 v[34:37], v[210:213], v[114:117], v[34:37]
	v_exp_f32_e32 v86, v86
	v_mfma_f32_16x16x32_bf16 v[38:41], v[210:213], v[118:121], v[38:41]
	ds_read_b64_tr_b16 v[210:211], v238 offset:57344
	ds_read_b64_tr_b16 v[212:213], v238 offset:61440
	v_exp_f32_e32 v87, v87
	s_waitcnt lgkmcnt(10)
	v_mfma_f32_16x16x32_bf16 v[42:45], v[214:217], v[114:117], v[42:45]
	v_exp_f32_e32 v88, v88
	v_mfma_f32_16x16x32_bf16 v[46:49], v[214:217], v[118:121], v[46:49]
	ds_read_b64_tr_b16 v[214:215], v239 offset:57344
	ds_read_b64_tr_b16 v[216:217], v239 offset:61440
	v_exp_f32_e32 v89, v89
	s_waitcnt lgkmcnt(10)
	v_mfma_f32_16x16x32_bf16 v[50:53], v[218:221], v[114:117], v[50:53]
	v_exp_f32_e32 v90, v90
	v_mfma_f32_16x16x32_bf16 v[54:57], v[218:221], v[118:121], v[54:57]
	ds_read_b64_tr_b16 v[218:219], v240 offset:57344
	ds_read_b64_tr_b16 v[220:221], v240 offset:61440
	v_exp_f32_e32 v91, v91
	s_waitcnt lgkmcnt(10)
	v_mfma_f32_16x16x32_bf16 v[58:61], v[222:225], v[114:117], v[58:61]
	v_exp_f32_e32 v92, v92
	v_mfma_f32_16x16x32_bf16 v[62:65], v[222:225], v[118:121], v[62:65]
	ds_read_b64_tr_b16 v[222:223], v241 offset:57344
	ds_read_b64_tr_b16 v[224:225], v241 offset:61440
	v_exp_f32_e32 v93, v93
	s_waitcnt lgkmcnt(10)
	v_mfma_f32_16x16x32_bf16 v[66:69], v[202:205], v[114:117], v[66:69]
	v_exp_f32_e32 v94, v94
	v_mfma_f32_16x16x32_bf16 v[70:73], v[202:205], v[118:121], v[70:73]
	ds_read_b64_tr_b16 v[202:203], v242 offset:57344
	ds_read_b64_tr_b16 v[204:205], v242 offset:61440
	v_exp_f32_e32 v95, v95
	s_waitcnt lgkmcnt(10)
	v_mfma_f32_16x16x32_bf16 v[74:77], v[206:209], v[114:117], v[74:77]
	v_exp_f32_e32 v96, v96
	v_mfma_f32_16x16x32_bf16 v[78:81], v[206:209], v[118:121], v[78:81]
	ds_read_b64_tr_b16 v[206:207], v243 offset:57344
	ds_read_b64_tr_b16 v[208:209], v243 offset:61440
	v_exp_f32_e32 v97, v97
	s_waitcnt lgkmcnt(10)
	v_mfma_f32_16x16x32_bf16 v[18:21], v[210:213], v[130:133], v[18:21]
	v_exp_f32_e32 v98, v98
	v_mfma_f32_16x16x32_bf16 v[22:25], v[210:213], v[134:137], v[22:25]
	ds_read_b64_tr_b16 v[210:211], v244 offset:57344
	ds_read_b64_tr_b16 v[212:213], v244 offset:61440
	v_exp_f32_e32 v99, v99
	s_waitcnt lgkmcnt(10)
	v_mfma_f32_16x16x32_bf16 v[26:29], v[214:217], v[130:133], v[26:29]
	v_exp_f32_e32 v100, v100
	v_mfma_f32_16x16x32_bf16 v[30:33], v[214:217], v[134:137], v[30:33]
	ds_read_b64_tr_b16 v[214:215], v245 offset:57344
	ds_read_b64_tr_b16 v[216:217], v245 offset:61440
	v_exp_f32_e32 v101, v101
	s_waitcnt lgkmcnt(10)
	v_mfma_f32_16x16x32_bf16 v[34:37], v[218:221], v[130:133], v[34:37]
	v_exp_f32_e32 v102, v102
	v_mfma_f32_16x16x32_bf16 v[38:41], v[218:221], v[134:137], v[38:41]
	v_exp_f32_e32 v103, v103
	s_waitcnt lgkmcnt(8)
	v_mfma_f32_16x16x32_bf16 v[42:45], v[222:225], v[130:133], v[42:45]
	v_exp_f32_e32 v104, v104
	v_mfma_f32_16x16x32_bf16 v[46:49], v[222:225], v[134:137], v[46:49]
	v_exp_f32_e32 v105, v105
	s_waitcnt lgkmcnt(6)
	v_mfma_f32_16x16x32_bf16 v[50:53], v[202:205], v[130:133], v[50:53]
	v_exp_f32_e32 v106, v106
	ds_read_b128 v[178:181], v234 offset:16384
	v_mfma_f32_16x16x32_bf16 v[54:57], v[202:205], v[134:137], v[54:57]
	v_exp_f32_e32 v107, v107
	s_waitcnt lgkmcnt(5)
	v_mfma_f32_16x16x32_bf16 v[58:61], v[206:209], v[130:133], v[58:61]
	v_exp_f32_e32 v108, v108
	ds_read_b128 v[182:185], v234 offset:20480
	v_mfma_f32_16x16x32_bf16 v[62:65], v[206:209], v[134:137], v[62:65]
	v_exp_f32_e32 v109, v109
	s_waitcnt lgkmcnt(4)
	v_mfma_f32_16x16x32_bf16 v[66:69], v[210:213], v[130:133], v[66:69]
	v_exp_f32_e32 v110, v110
	ds_read_b128 v[186:189], v234 offset:24576
	v_mfma_f32_16x16x32_bf16 v[70:73], v[210:213], v[134:137], v[70:73]
	v_exp_f32_e32 v111, v111
	s_waitcnt lgkmcnt(3)
	v_mfma_f32_16x16x32_bf16 v[74:77], v[214:217], v[130:133], v[74:77]
	v_exp_f32_e32 v112, v112
	ds_read_b128 v[190:193], v234 offset:28672
	v_mfma_f32_16x16x32_bf16 v[78:81], v[214:217], v[134:137], v[78:81]
	v_exp_f32_e32 v113, v113
	s_waitcnt vmcnt(4)
	s_add_i32 s15, s15, 1
	s_cmp_lt_u32 s15, 32
	s_cbranch_scc1 .Lattn_loop
	s_barrier
; __device__ __forceinline__ void finishSM(f32x16& p0, f32x16& p1, float& l_reg, bf16x8& pa0, bf16x8& pa1, bf16x8& pa2, bf16x8& pa3) {
;   for (int r = 0; r < 16; ++r) p1[r] = __builtin_amdgcn_exp2f(p1[r]);
;   float ps = 0; for (int r = 0; r < 16; ++r) ps += p0[r]; for (int r = 0; r < 16; ++r) ps += p1[r];
;   { auto rr = __builtin_amdgcn_permlane32_swap(__float_as_uint(ps), __float_as_uint(ps), false, false);
;     ps = __uint_as_float(rr[0]) + __uint_as_float(rr[1]); }
;   l_reg += ps;
;     ...
;   PK4(p0, 0, pa0); PK4(p0, 8, pa1); PK4(p1, 0, pa2); PK4(p1, 8, pa3);
;     ...
; }
; __device__ __forceinline__ void qkt(f32x16& p0, f32x16& p1, const bf16* Ks, const bf16x8* qr, int r32, int hi, const f32x16& negm) {
; #pragma unroll
;   for (int d0 = 0; d0 < 8; ++d0) { int cb = (d0 * 16 + hi * 8) * 2;
;     bf16x8 b0 = *reinterpret_cast<const bf16x8*>((const char*)Ks + KSWZ(r32, cb));
;     bf16x8 b1 = *reinterpret_cast<const bf16x8*>((const char*)Ks + KSWZ(32 + r32, cb));
;     if (d0 == 0) { p0 = __builtin_amdgcn_mfma_f32_32x32x16_bf16(b0, qr[0], negm, 0, 0, 0); p1 = __builtin_amdgcn_mfma_f32_32x32x16_bf16(b1, qr[0], negm, 0, 0, 0); }
;     else { p0 = __builtin_amdgcn_mfma_f32_32x32x16_bf16(b0, qr[d0], p0, 0, 0, 0); p1 = __builtin_amdgcn_mfma_f32_32x32x16_bf16(b1, qr[d0], p1, 0, 0, 0); } }
; }
	s_waitcnt lgkmcnt(3)
	v_mfma_f32_16x16x32_bf16 v[114:117], v[178:181], v[146:149], v[2:5]
	v_add_f32_e32 v250, v82, v250
	s_add_u32 s98, s98, 0x8000
	s_addc_u32 s99, s99, 0
	s_add_u32 s100, s100, 0x8000
	s_addc_u32 s101, s101, 0
	v_mfma_f32_16x16x32_bf16 v[118:121], v[178:181], v[162:165], v[2:5]
	ds_read_b128 v[178:181], v235 offset:16384
	v_add_f32_e32 v250, v83, v250
	v_add_f32_e32 v250, v84, v250
	s_waitcnt lgkmcnt(3)
	v_mfma_f32_16x16x32_bf16 v[122:125], v[182:185], v[146:149], v[2:5]
	v_add_f32_e32 v250, v85, v250
	v_mfma_f32_16x16x32_bf16 v[126:129], v[182:185], v[162:165], v[2:5]
	ds_read_b128 v[182:185], v235 offset:20480
	v_add_f32_e32 v250, v90, v250
	v_add_f32_e32 v250, v91, v250
	s_waitcnt lgkmcnt(3)
	v_mfma_f32_16x16x32_bf16 v[130:133], v[186:189], v[146:149], v[2:5]
	v_add_f32_e32 v250, v92, v250
	s_add_u32 m0, s80, 49152
	s_nop 0
	global_load_lds_dwordx4 v248, s[100:101]
	v_mfma_f32_16x16x32_bf16 v[134:137], v[186:189], v[162:165], v[2:5]
	ds_read_b128 v[186:189], v235 offset:24576
	v_add_f32_e32 v250, v93, v250
	v_cvt_pk_bf16_f32 v82, v82, v83
	s_waitcnt lgkmcnt(3)
	v_mfma_f32_16x16x32_bf16 v[138:141], v[190:193], v[146:149], v[2:5]
	v_cvt_pk_bf16_f32 v83, v84, v85
	v_mfma_f32_16x16x32_bf16 v[142:145], v[190:193], v[162:165], v[2:5]
	ds_read_b128 v[190:193], v235 offset:28672
	v_cvt_pk_bf16_f32 v84, v90, v91
	v_cvt_pk_bf16_f32 v85, v92, v93
	s_waitcnt lgkmcnt(3)
	v_mfma_f32_16x16x32_bf16 v[114:117], v[178:181], v[150:153], v[114:117]
	v_add_f32_e32 v251, v86, v251
	v_mfma_f32_16x16x32_bf16 v[118:121], v[178:181], v[166:169], v[118:121]
	ds_read_b128 v[178:181], v236 offset:16384
	v_add_f32_e32 v251, v87, v251
	v_add_f32_e32 v251, v88, v251
	s_waitcnt lgkmcnt(3)
	v_mfma_f32_16x16x32_bf16 v[122:125], v[182:185], v[150:153], v[122:125]
	v_add_f32_e32 v251, v89, v251
	v_mfma_f32_16x16x32_bf16 v[126:129], v[182:185], v[166:169], v[126:129]
	ds_read_b128 v[182:185], v236 offset:20480
	v_add_f32_e32 v251, v94, v251
	v_add_f32_e32 v251, v95, v251
	s_waitcnt lgkmcnt(3)
	v_mfma_f32_16x16x32_bf16 v[130:133], v[186:189], v[150:153], v[130:133]
	v_add_f32_e32 v251, v96, v251
	s_add_u32 m0, s80, 50176
	s_nop 0
	global_load_lds_dwordx4 v249, s[100:101]
	v_mfma_f32_16x16x32_bf16 v[134:137], v[186:189], v[166:169], v[134:137]
	ds_read_b128 v[186:189], v236 offset:24576
	v_add_f32_e32 v251, v97, v251
	v_cvt_pk_bf16_f32 v86, v86, v87
	s_waitcnt lgkmcnt(3)
	v_mfma_f32_16x16x32_bf16 v[138:141], v[190:193], v[150:153], v[138:141]
	v_cvt_pk_bf16_f32 v87, v88, v89
	v_mfma_f32_16x16x32_bf16 v[142:145], v[190:193], v[166:169], v[142:145]
	ds_read_b128 v[190:193], v236 offset:28672
	v_cvt_pk_bf16_f32 v88, v94, v95
	v_cvt_pk_bf16_f32 v89, v96, v97
	s_waitcnt lgkmcnt(3)
	v_mfma_f32_16x16x32_bf16 v[114:117], v[178:181], v[154:157], v[114:117]
	v_add_f32_e32 v250, v98, v250
	v_mfma_f32_16x16x32_bf16 v[118:121], v[178:181], v[170:173], v[118:121]
	ds_read_b128 v[178:181], v237 offset:16384
	v_add_f32_e32 v250, v99, v250
	v_add_f32_e32 v250, v100, v250
	s_waitcnt lgkmcnt(3)
	v_mfma_f32_16x16x32_bf16 v[122:125], v[182:185], v[154:157], v[122:125]
	v_add_f32_e32 v250, v101, v250
	v_mfma_f32_16x16x32_bf16 v[126:129], v[182:185], v[170:173], v[126:129]
	ds_read_b128 v[182:185], v237 offset:20480
	v_add_f32_e32 v250, v106, v250
	v_add_f32_e32 v250, v107, v250
	s_waitcnt lgkmcnt(3)
	v_mfma_f32_16x16x32_bf16 v[130:133], v[186:189], v[154:157], v[130:133]
	v_add_f32_e32 v250, v108, v250
	ds_read_b64_tr_b16 v[202:203], v238 offset:0
	ds_read_b64_tr_b16 v[204:205], v238 offset:4096
	v_mfma_f32_16x16x32_bf16 v[134:137], v[186:189], v[170:173], v[134:137]
	ds_read_b128 v[186:189], v237 offset:24576
	v_add_f32_e32 v250, v109, v250
	v_cvt_pk_bf16_f32 v98, v98, v99
	s_waitcnt lgkmcnt(5)
	v_mfma_f32_16x16x32_bf16 v[138:141], v[190:193], v[154:157], v[138:141]
	v_cvt_pk_bf16_f32 v99, v100, v101
	ds_read_b64_tr_b16 v[206:207], v239 offset:0
	ds_read_b64_tr_b16 v[208:209], v239 offset:4096
	v_mfma_f32_16x16x32_bf16 v[142:145], v[190:193], v[170:173], v[142:145]
	ds_read_b128 v[190:193], v237 offset:28672
	v_cvt_pk_bf16_f32 v100, v106, v107
	v_cvt_pk_bf16_f32 v101, v108, v109
	s_waitcnt lgkmcnt(7)
	v_mfma_f32_16x16x32_bf16 v[114:117], v[178:181], v[158:161], v[114:117]
	v_add_f32_e32 v251, v102, v251
	ds_read_b64_tr_b16 v[210:211], v240 offset:0
	ds_read_b64_tr_b16 v[212:213], v240 offset:4096
	v_mfma_f32_16x16x32_bf16 v[118:121], v[178:181], v[174:177], v[118:121]
	v_add_f32_e32 v251, v103, v251
	v_add_f32_e32 v251, v104, v251
	s_waitcnt lgkmcnt(8)
	v_mfma_f32_16x16x32_bf16 v[122:125], v[182:185], v[158:161], v[122:125]
	v_add_f32_e32 v251, v105, v251
	ds_read_b64_tr_b16 v[214:215], v241 offset:0
	ds_read_b64_tr_b16 v[216:217], v241 offset:4096
	v_mfma_f32_16x16x32_bf16 v[126:129], v[182:185], v[174:177], v[126:129]
	v_add_f32_e32 v251, v110, v251
	v_add_f32_e32 v251, v111, v251
	s_waitcnt lgkmcnt(7)
	v_mfma_f32_16x16x32_bf16 v[130:133], v[186:189], v[158:161], v[130:133]
	v_add_f32_e32 v251, v112, v251
	ds_read_b64_tr_b16 v[218:219], v242 offset:0
	ds_read_b64_tr_b16 v[220:221], v242 offset:4096
	v_mfma_f32_16x16x32_bf16 v[134:137], v[186:189], v[174:177], v[134:137]
	v_add_f32_e32 v251, v113, v251
	v_cvt_pk_bf16_f32 v102, v102, v103
	s_waitcnt lgkmcnt(6)
; #define SBAR() __builtin_amdgcn_sched_barrier(0)
; __device__ __forceinline__ void partialSM(f32x16& p0, f32x16& p1, float mC) {
;   (void)mC; (void)p1;
;   for (int r = 0; r < 16; ++r) p0[r] = __builtin_amdgcn_exp2f(p0[r]);
; }
; template <int D0> __device__ __forceinline__ void pv_one(f32x16& od, int vb, bf16x8 pa0, bf16x8 pa1, bf16x8 pa2, bf16x8 pa3) {
;   const s16x4 l0 = tr_read<v_rd_off(D0, 0, 0)>(vb), h0 = tr_read<v_rd_off(D0, 0, 1)>(vb), l1 = tr_read<v_rd_off(D0, 1, 0)>(vb), h1 = tr_read<v_rd_off(D0, 1, 1)>(vb);
;   const s16x4 l2 = tr_read<v_rd_off(D0, 2, 0)>(vb), h2 = tr_read<v_rd_off(D0, 2, 1)>(vb), l3 = tr_read<v_rd_off(D0, 3, 0)>(vb), h3 = tr_read<v_rd_off(D0, 3, 1)>(vb);
;   asm volatile("s_waitcnt lgkmcnt(0)" ::: "memory"); SBAR();
;     ...
;   od = __builtin_amdgcn_mfma_f32_32x32x16_bf16(pa0, PK(l0, h0), od, 0, 0, 0);
;   od = __builtin_amdgcn_mfma_f32_32x32x16_bf16(pa1, PK(l1, h1), od, 0, 0, 0);
;   od = __builtin_amdgcn_mfma_f32_32x32x16_bf16(pa2, PK(l2, h2), od, 0, 0, 0);
;   od = __builtin_amdgcn_mfma_f32_32x32x16_bf16(pa3, PK(l3, h3), od, 0, 0, 0);
;     ...
; }
; __device__ __forceinline__ void pv_d0(f32x16* o, int vb, bf16x8 pa0, bf16x8 pa1, bf16x8 pa2, bf16x8 pa3) {
;   pv_one<0>(o[0], vb, pa0, pa1, pa2, pa3); pv_one<1>(o[1], vb, pa0, pa1, pa2, pa3); pv_one<2>(o[2], vb, pa0, pa1, pa2, pa3); pv_one<3>(o[3], vb, pa0, pa1, pa2, pa3);
	v_mfma_f32_16x16x32_bf16 v[138:141], v[190:193], v[158:161], v[138:141]
	v_cvt_pk_bf16_f32 v103, v104, v105
	ds_read_b64_tr_b16 v[222:223], v243 offset:0
	ds_read_b64_tr_b16 v[224:225], v243 offset:4096
	v_mfma_f32_16x16x32_bf16 v[142:145], v[190:193], v[174:177], v[142:145]
	v_cvt_pk_bf16_f32 v104, v110, v111
	v_cvt_pk_bf16_f32 v105, v112, v113
	v_mfma_f32_16x16x32_bf16 v[18:21], v[202:205], v[82:85], v[18:21]
	v_exp_f32_e32 v114, v114
	v_mfma_f32_16x16x32_bf16 v[22:25], v[202:205], v[86:89], v[22:25]
	ds_read_b64_tr_b16 v[202:203], v244 offset:0
	ds_read_b64_tr_b16 v[204:205], v244 offset:4096
	v_exp_f32_e32 v115, v115
	v_mfma_f32_16x16x32_bf16 v[26:29], v[206:209], v[82:85], v[26:29]
	v_exp_f32_e32 v116, v116
	v_mfma_f32_16x16x32_bf16 v[30:33], v[206:209], v[86:89], v[30:33]
	ds_read_b64_tr_b16 v[206:207], v245 offset:0
	ds_read_b64_tr_b16 v[208:209], v245 offset:4096
	v_exp_f32_e32 v117, v117
	s_waitcnt lgkmcnt(10)
	v_mfma_f32_16x16x32_bf16 v[34:37], v[210:213], v[82:85], v[34:37]
	v_exp_f32_e32 v118, v118
	v_mfma_f32_16x16x32_bf16 v[38:41], v[210:213], v[86:89], v[38:41]
	ds_read_b64_tr_b16 v[210:211], v238 offset:8192
	ds_read_b64_tr_b16 v[212:213], v238 offset:12288
	v_exp_f32_e32 v119, v119
	s_waitcnt lgkmcnt(10)
	v_mfma_f32_16x16x32_bf16 v[42:45], v[214:217], v[82:85], v[42:45]
	v_exp_f32_e32 v120, v120
	v_mfma_f32_16x16x32_bf16 v[46:49], v[214:217], v[86:89], v[46:49]
	ds_read_b64_tr_b16 v[214:215], v239 offset:8192
	ds_read_b64_tr_b16 v[216:217], v239 offset:12288
	v_exp_f32_e32 v121, v121
	s_waitcnt lgkmcnt(10)
	v_mfma_f32_16x16x32_bf16 v[50:53], v[218:221], v[82:85], v[50:53]
	v_exp_f32_e32 v122, v122
	v_mfma_f32_16x16x32_bf16 v[54:57], v[218:221], v[86:89], v[54:57]
	ds_read_b64_tr_b16 v[218:219], v240 offset:8192
	ds_read_b64_tr_b16 v[220:221], v240 offset:12288
	v_exp_f32_e32 v123, v123
	s_waitcnt lgkmcnt(10)
	v_mfma_f32_16x16x32_bf16 v[58:61], v[222:225], v[82:85], v[58:61]
	v_exp_f32_e32 v124, v124
	v_mfma_f32_16x16x32_bf16 v[62:65], v[222:225], v[86:89], v[62:65]
	ds_read_b64_tr_b16 v[222:223], v241 offset:8192
	ds_read_b64_tr_b16 v[224:225], v241 offset:12288
	v_exp_f32_e32 v125, v125
	s_waitcnt lgkmcnt(10)
	v_mfma_f32_16x16x32_bf16 v[66:69], v[202:205], v[82:85], v[66:69]
	v_exp_f32_e32 v126, v126
	v_mfma_f32_16x16x32_bf16 v[70:73], v[202:205], v[86:89], v[70:73]
	ds_read_b64_tr_b16 v[202:203], v242 offset:8192
	ds_read_b64_tr_b16 v[204:205], v242 offset:12288
	v_exp_f32_e32 v127, v127
	s_waitcnt lgkmcnt(10)
	v_mfma_f32_16x16x32_bf16 v[74:77], v[206:209], v[82:85], v[74:77]
	v_exp_f32_e32 v128, v128
	v_mfma_f32_16x16x32_bf16 v[78:81], v[206:209], v[86:89], v[78:81]
	ds_read_b64_tr_b16 v[206:207], v243 offset:8192
	ds_read_b64_tr_b16 v[208:209], v243 offset:12288
	v_exp_f32_e32 v129, v129
	s_waitcnt lgkmcnt(10)
	v_mfma_f32_16x16x32_bf16 v[18:21], v[210:213], v[98:101], v[18:21]
	v_exp_f32_e32 v130, v130
	v_mfma_f32_16x16x32_bf16 v[22:25], v[210:213], v[102:105], v[22:25]
	ds_read_b64_tr_b16 v[210:211], v244 offset:8192
	ds_read_b64_tr_b16 v[212:213], v244 offset:12288
	v_exp_f32_e32 v131, v131
	s_waitcnt lgkmcnt(10)
	v_mfma_f32_16x16x32_bf16 v[26:29], v[214:217], v[98:101], v[26:29]
	v_exp_f32_e32 v132, v132
	v_mfma_f32_16x16x32_bf16 v[30:33], v[214:217], v[102:105], v[30:33]
	ds_read_b64_tr_b16 v[214:215], v245 offset:8192
	ds_read_b64_tr_b16 v[216:217], v245 offset:12288
	v_exp_f32_e32 v133, v133
	s_waitcnt lgkmcnt(10)
	v_mfma_f32_16x16x32_bf16 v[34:37], v[218:221], v[98:101], v[34:37]
	v_exp_f32_e32 v134, v134
	v_mfma_f32_16x16x32_bf16 v[38:41], v[218:221], v[102:105], v[38:41]
	v_exp_f32_e32 v135, v135
	s_waitcnt lgkmcnt(8)
	v_mfma_f32_16x16x32_bf16 v[42:45], v[222:225], v[98:101], v[42:45]
	v_exp_f32_e32 v136, v136
	v_mfma_f32_16x16x32_bf16 v[46:49], v[222:225], v[102:105], v[46:49]
	v_exp_f32_e32 v137, v137
	s_waitcnt lgkmcnt(6)
	v_mfma_f32_16x16x32_bf16 v[50:53], v[202:205], v[98:101], v[50:53]
	v_exp_f32_e32 v138, v138
	ds_read_b128 v[178:181], v234 offset:32768
	v_mfma_f32_16x16x32_bf16 v[54:57], v[202:205], v[102:105], v[54:57]
	v_exp_f32_e32 v139, v139
	s_waitcnt lgkmcnt(5)
	v_mfma_f32_16x16x32_bf16 v[58:61], v[206:209], v[98:101], v[58:61]
	v_exp_f32_e32 v140, v140
	ds_read_b128 v[182:185], v234 offset:36864
	v_mfma_f32_16x16x32_bf16 v[62:65], v[206:209], v[102:105], v[62:65]
	v_exp_f32_e32 v141, v141
	s_waitcnt lgkmcnt(4)
	v_mfma_f32_16x16x32_bf16 v[66:69], v[210:213], v[98:101], v[66:69]
	v_exp_f32_e32 v142, v142
	ds_read_b128 v[186:189], v234 offset:40960
	v_mfma_f32_16x16x32_bf16 v[70:73], v[210:213], v[102:105], v[70:73]
	v_exp_f32_e32 v143, v143
	s_waitcnt lgkmcnt(3)
	v_mfma_f32_16x16x32_bf16 v[74:77], v[214:217], v[98:101], v[74:77]
	v_exp_f32_e32 v144, v144
	ds_read_b128 v[190:193], v234 offset:45056
	v_mfma_f32_16x16x32_bf16 v[78:81], v[214:217], v[102:105], v[78:81]
	v_exp_f32_e32 v145, v145
	s_waitcnt vmcnt(2)
	s_barrier
; #define SBAR() __builtin_amdgcn_sched_barrier(0)
; __device__ __forceinline__ void qkt(f32x16& p0, f32x16& p1, const bf16* Ks, const bf16x8* qr, int r32, int hi, const f32x16& negm) {
; #pragma unroll
;   for (int d0 = 0; d0 < 8; ++d0) { int cb = (d0 * 16 + hi * 8) * 2;
;     bf16x8 b0 = *reinterpret_cast<const bf16x8*>((const char*)Ks + KSWZ(r32, cb));
;     bf16x8 b1 = *reinterpret_cast<const bf16x8*>((const char*)Ks + KSWZ(32 + r32, cb));
;     if (d0 == 0) { p0 = __builtin_amdgcn_mfma_f32_32x32x16_bf16(b0, qr[0], negm, 0, 0, 0); p1 = __builtin_amdgcn_mfma_f32_32x32x16_bf16(b1, qr[0], negm, 0, 0, 0); }
;     else { p0 = __builtin_amdgcn_mfma_f32_32x32x16_bf16(b0, qr[d0], p0, 0, 0, 0); p1 = __builtin_amdgcn_mfma_f32_32x32x16_bf16(b1, qr[d0], p1, 0, 0, 0); } }
; }
; template <int D0> __device__ __forceinline__ void pv_one(f32x16& od, int vb, bf16x8 pa0, bf16x8 pa1, bf16x8 pa2, bf16x8 pa3) {
;   const s16x4 l0 = tr_read<v_rd_off(D0, 0, 0)>(vb), h0 = tr_read<v_rd_off(D0, 0, 1)>(vb), l1 = tr_read<v_rd_off(D0, 1, 0)>(vb), h1 = tr_read<v_rd_off(D0, 1, 1)>(vb);
;   const s16x4 l2 = tr_read<v_rd_off(D0, 2, 0)>(vb), h2 = tr_read<v_rd_off(D0, 2, 1)>(vb), l3 = tr_read<v_rd_off(D0, 3, 0)>(vb), h3 = tr_read<v_rd_off(D0, 3, 1)>(vb);
;   asm volatile("s_waitcnt lgkmcnt(0)" ::: "memory"); SBAR();
;     ...
;   od = __builtin_amdgcn_mfma_f32_32x32x16_bf16(pa0, PK(l0, h0), od, 0, 0, 0);
;   od = __builtin_amdgcn_mfma_f32_32x32x16_bf16(pa1, PK(l1, h1), od, 0, 0, 0);
;   od = __builtin_amdgcn_mfma_f32_32x32x16_bf16(pa2, PK(l2, h2), od, 0, 0, 0);
;   od = __builtin_amdgcn_mfma_f32_32x32x16_bf16(pa3, PK(l3, h3), od, 0, 0, 0);
;     ...
; }
; __device__ __forceinline__ void pv_d0(f32x16* o, int vb, bf16x8 pa0, bf16x8 pa1, bf16x8 pa2, bf16x8 pa3) {
;   pv_one<0>(o[0], vb, pa0, pa1, pa2, pa3); pv_one<1>(o[1], vb, pa0, pa1, pa2, pa3); pv_one<2>(o[2], vb, pa0, pa1, pa2, pa3); pv_one<3>(o[3], vb, pa0, pa1, pa2, pa3);
	s_waitcnt lgkmcnt(3)
	v_mfma_f32_16x16x32_bf16 v[82:85], v[178:181], v[146:149], v[2:5]
	v_add_f32_e32 v250, v114, v250
	v_mfma_f32_16x16x32_bf16 v[86:89], v[178:181], v[162:165], v[2:5]
	ds_read_b128 v[178:181], v235 offset:32768
	v_add_f32_e32 v250, v115, v250
	v_add_f32_e32 v250, v116, v250
	s_waitcnt lgkmcnt(3)
	v_mfma_f32_16x16x32_bf16 v[90:93], v[182:185], v[146:149], v[2:5]
	v_add_f32_e32 v250, v117, v250
	v_mfma_f32_16x16x32_bf16 v[94:97], v[182:185], v[162:165], v[2:5]
	ds_read_b128 v[182:185], v235 offset:36864
	v_add_f32_e32 v250, v122, v250
	v_add_f32_e32 v250, v123, v250
	s_waitcnt lgkmcnt(3)
	v_mfma_f32_16x16x32_bf16 v[98:101], v[186:189], v[146:149], v[2:5]
	v_add_f32_e32 v250, v124, v250
	v_mfma_f32_16x16x32_bf16 v[102:105], v[186:189], v[162:165], v[2:5]
	ds_read_b128 v[186:189], v235 offset:40960
	v_add_f32_e32 v250, v125, v250
	v_cvt_pk_bf16_f32 v114, v114, v115
	s_waitcnt lgkmcnt(3)
	v_mfma_f32_16x16x32_bf16 v[106:109], v[190:193], v[146:149], v[2:5]
	v_cvt_pk_bf16_f32 v115, v116, v117
	v_mfma_f32_16x16x32_bf16 v[110:113], v[190:193], v[162:165], v[2:5]
	ds_read_b128 v[190:193], v235 offset:45056
	v_cvt_pk_bf16_f32 v116, v122, v123
	v_cvt_pk_bf16_f32 v117, v124, v125
	s_waitcnt lgkmcnt(3)
	v_mfma_f32_16x16x32_bf16 v[82:85], v[178:181], v[150:153], v[82:85]
	v_add_f32_e32 v251, v118, v251
	v_mfma_f32_16x16x32_bf16 v[86:89], v[178:181], v[166:169], v[86:89]
	ds_read_b128 v[178:181], v236 offset:32768
	v_add_f32_e32 v251, v119, v251
	v_add_f32_e32 v251, v120, v251
	s_waitcnt lgkmcnt(3)
	v_mfma_f32_16x16x32_bf16 v[90:93], v[182:185], v[150:153], v[90:93]
	v_add_f32_e32 v251, v121, v251
	v_mfma_f32_16x16x32_bf16 v[94:97], v[182:185], v[166:169], v[94:97]
	ds_read_b128 v[182:185], v236 offset:36864
	v_add_f32_e32 v251, v126, v251
	v_add_f32_e32 v251, v127, v251
	s_waitcnt lgkmcnt(3)
	v_mfma_f32_16x16x32_bf16 v[98:101], v[186:189], v[150:153], v[98:101]
	v_add_f32_e32 v251, v128, v251
	v_mfma_f32_16x16x32_bf16 v[102:105], v[186:189], v[166:169], v[102:105]
	ds_read_b128 v[186:189], v236 offset:40960
	v_add_f32_e32 v251, v129, v251
	v_cvt_pk_bf16_f32 v118, v118, v119
	s_waitcnt lgkmcnt(3)
	v_mfma_f32_16x16x32_bf16 v[106:109], v[190:193], v[150:153], v[106:109]
	v_cvt_pk_bf16_f32 v119, v120, v121
	v_mfma_f32_16x16x32_bf16 v[110:113], v[190:193], v[166:169], v[110:113]
	ds_read_b128 v[190:193], v236 offset:45056
	v_cvt_pk_bf16_f32 v120, v126, v127
	v_cvt_pk_bf16_f32 v121, v128, v129
	s_waitcnt lgkmcnt(3)
	v_mfma_f32_16x16x32_bf16 v[82:85], v[178:181], v[154:157], v[82:85]
	v_add_f32_e32 v250, v130, v250
	v_mfma_f32_16x16x32_bf16 v[86:89], v[178:181], v[170:173], v[86:89]
	ds_read_b128 v[178:181], v237 offset:32768
	v_add_f32_e32 v250, v131, v250
	v_add_f32_e32 v250, v132, v250
	s_waitcnt lgkmcnt(3)
	v_mfma_f32_16x16x32_bf16 v[90:93], v[182:185], v[154:157], v[90:93]
	v_add_f32_e32 v250, v133, v250
	v_mfma_f32_16x16x32_bf16 v[94:97], v[182:185], v[170:173], v[94:97]
	ds_read_b128 v[182:185], v237 offset:36864
	v_add_f32_e32 v250, v138, v250
	v_add_f32_e32 v250, v139, v250
	s_waitcnt lgkmcnt(3)
	v_mfma_f32_16x16x32_bf16 v[98:101], v[186:189], v[154:157], v[98:101]
	v_add_f32_e32 v250, v140, v250
	ds_read_b64_tr_b16 v[202:203], v238 offset:16384
	ds_read_b64_tr_b16 v[204:205], v238 offset:20480
	v_mfma_f32_16x16x32_bf16 v[102:105], v[186:189], v[170:173], v[102:105]
	ds_read_b128 v[186:189], v237 offset:40960
	v_add_f32_e32 v250, v141, v250
	v_cvt_pk_bf16_f32 v130, v130, v131
	s_waitcnt lgkmcnt(5)
	v_mfma_f32_16x16x32_bf16 v[106:109], v[190:193], v[154:157], v[106:109]
	v_cvt_pk_bf16_f32 v131, v132, v133
	ds_read_b64_tr_b16 v[206:207], v239 offset:16384
	ds_read_b64_tr_b16 v[208:209], v239 offset:20480
	v_mfma_f32_16x16x32_bf16 v[110:113], v[190:193], v[170:173], v[110:113]
	ds_read_b128 v[190:193], v237 offset:45056
	v_cvt_pk_bf16_f32 v132, v138, v139
	v_cvt_pk_bf16_f32 v133, v140, v141
	s_waitcnt lgkmcnt(7)
	v_mfma_f32_16x16x32_bf16 v[82:85], v[178:181], v[158:161], v[82:85]
	v_add_f32_e32 v251, v134, v251
	ds_read_b64_tr_b16 v[210:211], v240 offset:16384
	ds_read_b64_tr_b16 v[212:213], v240 offset:20480
	v_mfma_f32_16x16x32_bf16 v[86:89], v[178:181], v[174:177], v[86:89]
	v_add_f32_e32 v251, v135, v251
	v_add_f32_e32 v251, v136, v251
	s_waitcnt lgkmcnt(8)
	v_mfma_f32_16x16x32_bf16 v[90:93], v[182:185], v[158:161], v[90:93]
	v_add_f32_e32 v251, v137, v251
	ds_read_b64_tr_b16 v[214:215], v241 offset:16384
	ds_read_b64_tr_b16 v[216:217], v241 offset:20480
	v_mfma_f32_16x16x32_bf16 v[94:97], v[182:185], v[174:177], v[94:97]
	v_add_f32_e32 v251, v142, v251
	v_add_f32_e32 v251, v143, v251
	s_waitcnt lgkmcnt(7)
	v_mfma_f32_16x16x32_bf16 v[98:101], v[186:189], v[158:161], v[98:101]
	v_add_f32_e32 v251, v144, v251
	ds_read_b64_tr_b16 v[218:219], v242 offset:16384
	ds_read_b64_tr_b16 v[220:221], v242 offset:20480
	v_mfma_f32_16x16x32_bf16 v[102:105], v[186:189], v[174:177], v[102:105]
	v_add_f32_e32 v251, v145, v251
	v_cvt_pk_bf16_f32 v134, v134, v135
	s_waitcnt lgkmcnt(6)
	v_mfma_f32_16x16x32_bf16 v[106:109], v[190:193], v[158:161], v[106:109]
	v_cvt_pk_bf16_f32 v135, v136, v137
	ds_read_b64_tr_b16 v[222:223], v243 offset:16384
	ds_read_b64_tr_b16 v[224:225], v243 offset:20480
	v_mfma_f32_16x16x32_bf16 v[110:113], v[190:193], v[174:177], v[110:113]
	v_cvt_pk_bf16_f32 v136, v142, v143
	v_cvt_pk_bf16_f32 v137, v144, v145
	v_mfma_f32_16x16x32_bf16 v[18:21], v[202:205], v[114:117], v[18:21]
	v_exp_f32_e32 v82, v82
	v_mfma_f32_16x16x32_bf16 v[22:25], v[202:205], v[118:121], v[22:25]
	ds_read_b64_tr_b16 v[202:203], v244 offset:16384
	ds_read_b64_tr_b16 v[204:205], v244 offset:20480
	v_exp_f32_e32 v83, v83
	v_mfma_f32_16x16x32_bf16 v[26:29], v[206:209], v[114:117], v[26:29]
	v_exp_f32_e32 v84, v84
	v_mfma_f32_16x16x32_bf16 v[30:33], v[206:209], v[118:121], v[30:33]
	ds_read_b64_tr_b16 v[206:207], v245 offset:16384
	ds_read_b64_tr_b16 v[208:209], v245 offset:20480
	v_exp_f32_e32 v85, v85
	s_waitcnt lgkmcnt(10)
; #define SBAR() __builtin_amdgcn_sched_barrier(0)
; __device__ __forceinline__ void qkt(f32x16& p0, f32x16& p1, const bf16* Ks, const bf16x8* qr, int r32, int hi, const f32x16& negm) {
; #pragma unroll
;   for (int d0 = 0; d0 < 8; ++d0) { int cb = (d0 * 16 + hi * 8) * 2;
;     bf16x8 b0 = *reinterpret_cast<const bf16x8*>((const char*)Ks + KSWZ(r32, cb));
;     bf16x8 b1 = *reinterpret_cast<const bf16x8*>((const char*)Ks + KSWZ(32 + r32, cb));
;     if (d0 == 0) { p0 = __builtin_amdgcn_mfma_f32_32x32x16_bf16(b0, qr[0], negm, 0, 0, 0); p1 = __builtin_amdgcn_mfma_f32_32x32x16_bf16(b1, qr[0], negm, 0, 0, 0); }
;     else { p0 = __builtin_amdgcn_mfma_f32_32x32x16_bf16(b0, qr[d0], p0, 0, 0, 0); p1 = __builtin_amdgcn_mfma_f32_32x32x16_bf16(b1, qr[d0], p1, 0, 0, 0); } }
; }
; template <int D0> __device__ __forceinline__ void pv_one(f32x16& od, int vb, bf16x8 pa0, bf16x8 pa1, bf16x8 pa2, bf16x8 pa3) {
;   const s16x4 l0 = tr_read<v_rd_off(D0, 0, 0)>(vb), h0 = tr_read<v_rd_off(D0, 0, 1)>(vb), l1 = tr_read<v_rd_off(D0, 1, 0)>(vb), h1 = tr_read<v_rd_off(D0, 1, 1)>(vb);
;   const s16x4 l2 = tr_read<v_rd_off(D0, 2, 0)>(vb), h2 = tr_read<v_rd_off(D0, 2, 1)>(vb), l3 = tr_read<v_rd_off(D0, 3, 0)>(vb), h3 = tr_read<v_rd_off(D0, 3, 1)>(vb);
;   asm volatile("s_waitcnt lgkmcnt(0)" ::: "memory"); SBAR();
;     ...
;   od = __builtin_amdgcn_mfma_f32_32x32x16_bf16(pa0, PK(l0, h0), od, 0, 0, 0);
;   od = __builtin_amdgcn_mfma_f32_32x32x16_bf16(pa1, PK(l1, h1), od, 0, 0, 0);
;   od = __builtin_amdgcn_mfma_f32_32x32x16_bf16(pa2, PK(l2, h2), od, 0, 0, 0);
;   od = __builtin_amdgcn_mfma_f32_32x32x16_bf16(pa3, PK(l3, h3), od, 0, 0, 0);
;     ...
; }
; __device__ __forceinline__ void pv_d0(f32x16* o, int vb, bf16x8 pa0, bf16x8 pa1, bf16x8 pa2, bf16x8 pa3) {
;   pv_one<0>(o[0], vb, pa0, pa1, pa2, pa3); pv_one<1>(o[1], vb, pa0, pa1, pa2, pa3); pv_one<2>(o[2], vb, pa0, pa1, pa2, pa3); pv_one<3>(o[3], vb, pa0, pa1, pa2, pa3);
	v_mfma_f32_16x16x32_bf16 v[34:37], v[210:213], v[114:117], v[34:37]
	v_exp_f32_e32 v86, v86
	v_mfma_f32_16x16x32_bf16 v[38:41], v[210:213], v[118:121], v[38:41]
	ds_read_b64_tr_b16 v[210:211], v238 offset:24576
	ds_read_b64_tr_b16 v[212:213], v238 offset:28672
	v_exp_f32_e32 v87, v87
	s_waitcnt lgkmcnt(10)
	v_mfma_f32_16x16x32_bf16 v[42:45], v[214:217], v[114:117], v[42:45]
	v_exp_f32_e32 v88, v88
	v_mfma_f32_16x16x32_bf16 v[46:49], v[214:217], v[118:121], v[46:49]
	ds_read_b64_tr_b16 v[214:215], v239 offset:24576
	ds_read_b64_tr_b16 v[216:217], v239 offset:28672
	v_exp_f32_e32 v89, v89
	s_waitcnt lgkmcnt(10)
	v_mfma_f32_16x16x32_bf16 v[50:53], v[218:221], v[114:117], v[50:53]
	v_exp_f32_e32 v90, v90
	v_mfma_f32_16x16x32_bf16 v[54:57], v[218:221], v[118:121], v[54:57]
	ds_read_b64_tr_b16 v[218:219], v240 offset:24576
	ds_read_b64_tr_b16 v[220:221], v240 offset:28672
	v_exp_f32_e32 v91, v91
	s_waitcnt lgkmcnt(10)
	v_mfma_f32_16x16x32_bf16 v[58:61], v[222:225], v[114:117], v[58:61]
	v_exp_f32_e32 v92, v92
	v_mfma_f32_16x16x32_bf16 v[62:65], v[222:225], v[118:121], v[62:65]
	ds_read_b64_tr_b16 v[222:223], v241 offset:24576
	ds_read_b64_tr_b16 v[224:225], v241 offset:28672
	v_exp_f32_e32 v93, v93
	s_waitcnt lgkmcnt(10)
	v_mfma_f32_16x16x32_bf16 v[66:69], v[202:205], v[114:117], v[66:69]
	v_exp_f32_e32 v94, v94
	v_mfma_f32_16x16x32_bf16 v[70:73], v[202:205], v[118:121], v[70:73]
	ds_read_b64_tr_b16 v[202:203], v242 offset:24576
	ds_read_b64_tr_b16 v[204:205], v242 offset:28672
	v_exp_f32_e32 v95, v95
	s_waitcnt lgkmcnt(10)
	v_mfma_f32_16x16x32_bf16 v[74:77], v[206:209], v[114:117], v[74:77]
	v_exp_f32_e32 v96, v96
	v_mfma_f32_16x16x32_bf16 v[78:81], v[206:209], v[118:121], v[78:81]
	ds_read_b64_tr_b16 v[206:207], v243 offset:24576
	ds_read_b64_tr_b16 v[208:209], v243 offset:28672
	v_exp_f32_e32 v97, v97
	s_waitcnt lgkmcnt(10)
	v_mfma_f32_16x16x32_bf16 v[18:21], v[210:213], v[130:133], v[18:21]
	v_exp_f32_e32 v98, v98
	v_mfma_f32_16x16x32_bf16 v[22:25], v[210:213], v[134:137], v[22:25]
	ds_read_b64_tr_b16 v[210:211], v244 offset:24576
	ds_read_b64_tr_b16 v[212:213], v244 offset:28672
	v_exp_f32_e32 v99, v99
	s_waitcnt lgkmcnt(10)
	v_mfma_f32_16x16x32_bf16 v[26:29], v[214:217], v[130:133], v[26:29]
	v_exp_f32_e32 v100, v100
	v_mfma_f32_16x16x32_bf16 v[30:33], v[214:217], v[134:137], v[30:33]
	ds_read_b64_tr_b16 v[214:215], v245 offset:24576
	ds_read_b64_tr_b16 v[216:217], v245 offset:28672
	v_exp_f32_e32 v101, v101
	s_waitcnt lgkmcnt(10)
	v_mfma_f32_16x16x32_bf16 v[34:37], v[218:221], v[130:133], v[34:37]
	v_exp_f32_e32 v102, v102
	v_mfma_f32_16x16x32_bf16 v[38:41], v[218:221], v[134:137], v[38:41]
	v_exp_f32_e32 v103, v103
	s_waitcnt lgkmcnt(8)
	v_mfma_f32_16x16x32_bf16 v[42:45], v[222:225], v[130:133], v[42:45]
	v_exp_f32_e32 v104, v104
	v_mfma_f32_16x16x32_bf16 v[46:49], v[222:225], v[134:137], v[46:49]
	v_exp_f32_e32 v105, v105
	s_waitcnt lgkmcnt(6)
	v_mfma_f32_16x16x32_bf16 v[50:53], v[202:205], v[130:133], v[50:53]
	v_exp_f32_e32 v106, v106
	ds_read_b128 v[178:181], v234 offset:49152
	v_mfma_f32_16x16x32_bf16 v[54:57], v[202:205], v[134:137], v[54:57]
	v_exp_f32_e32 v107, v107
	s_waitcnt lgkmcnt(5)
	v_mfma_f32_16x16x32_bf16 v[58:61], v[206:209], v[130:133], v[58:61]
	v_exp_f32_e32 v108, v108
	ds_read_b128 v[182:185], v234 offset:53248
	v_mfma_f32_16x16x32_bf16 v[62:65], v[206:209], v[134:137], v[62:65]
	v_exp_f32_e32 v109, v109
	s_waitcnt lgkmcnt(4)
	v_mfma_f32_16x16x32_bf16 v[66:69], v[210:213], v[130:133], v[66:69]
	v_exp_f32_e32 v110, v110
	ds_read_b128 v[186:189], v234 offset:57344
	v_mfma_f32_16x16x32_bf16 v[70:73], v[210:213], v[134:137], v[70:73]
	v_exp_f32_e32 v111, v111
	s_waitcnt lgkmcnt(3)
	v_mfma_f32_16x16x32_bf16 v[74:77], v[214:217], v[130:133], v[74:77]
	v_exp_f32_e32 v112, v112
	ds_read_b128 v[190:193], v234 offset:61440
	v_mfma_f32_16x16x32_bf16 v[78:81], v[214:217], v[134:137], v[78:81]
	v_exp_f32_e32 v113, v113
	s_waitcnt vmcnt(0)
	s_barrier
	s_waitcnt lgkmcnt(3)
	v_mfma_f32_16x16x32_bf16 v[114:117], v[178:181], v[146:149], v[2:5]
	v_add_f32_e32 v250, v82, v250
	v_mfma_f32_16x16x32_bf16 v[118:121], v[178:181], v[162:165], v[2:5]
	ds_read_b128 v[178:181], v235 offset:49152
	v_add_f32_e32 v250, v83, v250
	v_add_f32_e32 v250, v84, v250
	s_waitcnt lgkmcnt(3)
	v_mfma_f32_16x16x32_bf16 v[122:125], v[182:185], v[146:149], v[2:5]
	v_add_f32_e32 v250, v85, v250
	v_mfma_f32_16x16x32_bf16 v[126:129], v[182:185], v[162:165], v[2:5]
	ds_read_b128 v[182:185], v235 offset:53248
	v_add_f32_e32 v250, v90, v250
	v_add_f32_e32 v250, v91, v250
	s_waitcnt lgkmcnt(3)
	v_mfma_f32_16x16x32_bf16 v[130:133], v[186:189], v[146:149], v[2:5]
	v_add_f32_e32 v250, v92, v250
	v_mfma_f32_16x16x32_bf16 v[134:137], v[186:189], v[162:165], v[2:5]
	ds_read_b128 v[186:189], v235 offset:57344
	v_add_f32_e32 v250, v93, v250
	v_cvt_pk_bf16_f32 v82, v82, v83
	s_waitcnt lgkmcnt(3)
	v_mfma_f32_16x16x32_bf16 v[138:141], v[190:193], v[146:149], v[2:5]
	v_cvt_pk_bf16_f32 v83, v84, v85
	v_mfma_f32_16x16x32_bf16 v[142:145], v[190:193], v[162:165], v[2:5]
	ds_read_b128 v[190:193], v235 offset:61440
	v_cvt_pk_bf16_f32 v84, v90, v91
	v_cvt_pk_bf16_f32 v85, v92, v93
	s_waitcnt lgkmcnt(3)
	v_mfma_f32_16x16x32_bf16 v[114:117], v[178:181], v[150:153], v[114:117]
	v_add_f32_e32 v251, v86, v251
	v_mfma_f32_16x16x32_bf16 v[118:121], v[178:181], v[166:169], v[118:121]
	ds_read_b128 v[178:181], v236 offset:49152
	v_add_f32_e32 v251, v87, v251
	v_add_f32_e32 v251, v88, v251
	s_waitcnt lgkmcnt(3)
	v_mfma_f32_16x16x32_bf16 v[122:125], v[182:185], v[150:153], v[122:125]
	v_add_f32_e32 v251, v89, v251
	v_mfma_f32_16x16x32_bf16 v[126:129], v[182:185], v[166:169], v[126:129]
	ds_read_b128 v[182:185], v236 offset:53248
	v_add_f32_e32 v251, v94, v251
	v_add_f32_e32 v251, v95, v251
	s_waitcnt lgkmcnt(3)
; #define SBAR() __builtin_amdgcn_sched_barrier(0)
; __device__ __forceinline__ void qkt(f32x16& p0, f32x16& p1, const bf16* Ks, const bf16x8* qr, int r32, int hi, const f32x16& negm) {
; #pragma unroll
;   for (int d0 = 0; d0 < 8; ++d0) { int cb = (d0 * 16 + hi * 8) * 2;
;     bf16x8 b0 = *reinterpret_cast<const bf16x8*>((const char*)Ks + KSWZ(r32, cb));
;     bf16x8 b1 = *reinterpret_cast<const bf16x8*>((const char*)Ks + KSWZ(32 + r32, cb));
;     if (d0 == 0) { p0 = __builtin_amdgcn_mfma_f32_32x32x16_bf16(b0, qr[0], negm, 0, 0, 0); p1 = __builtin_amdgcn_mfma_f32_32x32x16_bf16(b1, qr[0], negm, 0, 0, 0); }
;     else { p0 = __builtin_amdgcn_mfma_f32_32x32x16_bf16(b0, qr[d0], p0, 0, 0, 0); p1 = __builtin_amdgcn_mfma_f32_32x32x16_bf16(b1, qr[d0], p1, 0, 0, 0); } }
; }
; template <int D0> __device__ __forceinline__ void pv_one(f32x16& od, int vb, bf16x8 pa0, bf16x8 pa1, bf16x8 pa2, bf16x8 pa3) {
;   const s16x4 l0 = tr_read<v_rd_off(D0, 0, 0)>(vb), h0 = tr_read<v_rd_off(D0, 0, 1)>(vb), l1 = tr_read<v_rd_off(D0, 1, 0)>(vb), h1 = tr_read<v_rd_off(D0, 1, 1)>(vb);
;   const s16x4 l2 = tr_read<v_rd_off(D0, 2, 0)>(vb), h2 = tr_read<v_rd_off(D0, 2, 1)>(vb), l3 = tr_read<v_rd_off(D0, 3, 0)>(vb), h3 = tr_read<v_rd_off(D0, 3, 1)>(vb);
;   asm volatile("s_waitcnt lgkmcnt(0)" ::: "memory"); SBAR();
;     ...
;   od = __builtin_amdgcn_mfma_f32_32x32x16_bf16(pa0, PK(l0, h0), od, 0, 0, 0);
;   od = __builtin_amdgcn_mfma_f32_32x32x16_bf16(pa1, PK(l1, h1), od, 0, 0, 0);
;   od = __builtin_amdgcn_mfma_f32_32x32x16_bf16(pa2, PK(l2, h2), od, 0, 0, 0);
;   od = __builtin_amdgcn_mfma_f32_32x32x16_bf16(pa3, PK(l3, h3), od, 0, 0, 0);
;     ...
; }
; __device__ __forceinline__ void pv_d0(f32x16* o, int vb, bf16x8 pa0, bf16x8 pa1, bf16x8 pa2, bf16x8 pa3) {
;   pv_one<0>(o[0], vb, pa0, pa1, pa2, pa3); pv_one<1>(o[1], vb, pa0, pa1, pa2, pa3); pv_one<2>(o[2], vb, pa0, pa1, pa2, pa3); pv_one<3>(o[3], vb, pa0, pa1, pa2, pa3);
	v_mfma_f32_16x16x32_bf16 v[130:133], v[186:189], v[150:153], v[130:133]
	v_add_f32_e32 v251, v96, v251
	v_mfma_f32_16x16x32_bf16 v[134:137], v[186:189], v[166:169], v[134:137]
	ds_read_b128 v[186:189], v236 offset:57344
	v_add_f32_e32 v251, v97, v251
	v_cvt_pk_bf16_f32 v86, v86, v87
	s_waitcnt lgkmcnt(3)
	v_mfma_f32_16x16x32_bf16 v[138:141], v[190:193], v[150:153], v[138:141]
	v_cvt_pk_bf16_f32 v87, v88, v89
	v_mfma_f32_16x16x32_bf16 v[142:145], v[190:193], v[166:169], v[142:145]
	ds_read_b128 v[190:193], v236 offset:61440
	v_cvt_pk_bf16_f32 v88, v94, v95
	v_cvt_pk_bf16_f32 v89, v96, v97
	s_waitcnt lgkmcnt(3)
	v_mfma_f32_16x16x32_bf16 v[114:117], v[178:181], v[154:157], v[114:117]
	v_add_f32_e32 v250, v98, v250
	v_mfma_f32_16x16x32_bf16 v[118:121], v[178:181], v[170:173], v[118:121]
	ds_read_b128 v[178:181], v237 offset:49152
	v_add_f32_e32 v250, v99, v250
	v_add_f32_e32 v250, v100, v250
	s_waitcnt lgkmcnt(3)
	v_mfma_f32_16x16x32_bf16 v[122:125], v[182:185], v[154:157], v[122:125]
	v_add_f32_e32 v250, v101, v250
	v_mfma_f32_16x16x32_bf16 v[126:129], v[182:185], v[170:173], v[126:129]
	ds_read_b128 v[182:185], v237 offset:53248
	v_add_f32_e32 v250, v106, v250
	v_add_f32_e32 v250, v107, v250
	s_waitcnt lgkmcnt(3)
	v_mfma_f32_16x16x32_bf16 v[130:133], v[186:189], v[154:157], v[130:133]
	v_add_f32_e32 v250, v108, v250
	ds_read_b64_tr_b16 v[202:203], v238 offset:32768
	ds_read_b64_tr_b16 v[204:205], v238 offset:36864
	v_mfma_f32_16x16x32_bf16 v[134:137], v[186:189], v[170:173], v[134:137]
	ds_read_b128 v[186:189], v237 offset:57344
	v_add_f32_e32 v250, v109, v250
	v_cvt_pk_bf16_f32 v98, v98, v99
	s_waitcnt lgkmcnt(5)
	v_mfma_f32_16x16x32_bf16 v[138:141], v[190:193], v[154:157], v[138:141]
	v_cvt_pk_bf16_f32 v99, v100, v101
	ds_read_b64_tr_b16 v[206:207], v239 offset:32768
	ds_read_b64_tr_b16 v[208:209], v239 offset:36864
	v_mfma_f32_16x16x32_bf16 v[142:145], v[190:193], v[170:173], v[142:145]
	ds_read_b128 v[190:193], v237 offset:61440
	v_cvt_pk_bf16_f32 v100, v106, v107
	v_cvt_pk_bf16_f32 v101, v108, v109
	s_waitcnt lgkmcnt(7)
	v_mfma_f32_16x16x32_bf16 v[114:117], v[178:181], v[158:161], v[114:117]
	v_add_f32_e32 v251, v102, v251
	ds_read_b64_tr_b16 v[210:211], v240 offset:32768
	ds_read_b64_tr_b16 v[212:213], v240 offset:36864
	v_mfma_f32_16x16x32_bf16 v[118:121], v[178:181], v[174:177], v[118:121]
	v_add_f32_e32 v251, v103, v251
	v_add_f32_e32 v251, v104, v251
	s_waitcnt lgkmcnt(8)
	v_mfma_f32_16x16x32_bf16 v[122:125], v[182:185], v[158:161], v[122:125]
	v_add_f32_e32 v251, v105, v251
	ds_read_b64_tr_b16 v[214:215], v241 offset:32768
	ds_read_b64_tr_b16 v[216:217], v241 offset:36864
	v_mfma_f32_16x16x32_bf16 v[126:129], v[182:185], v[174:177], v[126:129]
	v_add_f32_e32 v251, v110, v251
	v_add_f32_e32 v251, v111, v251
	s_waitcnt lgkmcnt(7)
	v_mfma_f32_16x16x32_bf16 v[130:133], v[186:189], v[158:161], v[130:133]
	v_add_f32_e32 v251, v112, v251
	ds_read_b64_tr_b16 v[218:219], v242 offset:32768
	ds_read_b64_tr_b16 v[220:221], v242 offset:36864
	v_mfma_f32_16x16x32_bf16 v[134:137], v[186:189], v[174:177], v[134:137]
	v_add_f32_e32 v251, v113, v251
	v_cvt_pk_bf16_f32 v102, v102, v103
	s_waitcnt lgkmcnt(6)
	v_mfma_f32_16x16x32_bf16 v[138:141], v[190:193], v[158:161], v[138:141]
	v_cvt_pk_bf16_f32 v103, v104, v105
	ds_read_b64_tr_b16 v[222:223], v243 offset:32768
	ds_read_b64_tr_b16 v[224:225], v243 offset:36864
	v_mfma_f32_16x16x32_bf16 v[142:145], v[190:193], v[174:177], v[142:145]
	v_cvt_pk_bf16_f32 v104, v110, v111
	v_cvt_pk_bf16_f32 v105, v112, v113
	v_mfma_f32_16x16x32_bf16 v[18:21], v[202:205], v[82:85], v[18:21]
	v_exp_f32_e32 v114, v114
	v_mfma_f32_16x16x32_bf16 v[22:25], v[202:205], v[86:89], v[22:25]
	ds_read_b64_tr_b16 v[202:203], v244 offset:32768
	ds_read_b64_tr_b16 v[204:205], v244 offset:36864
	v_exp_f32_e32 v115, v115
	v_mfma_f32_16x16x32_bf16 v[26:29], v[206:209], v[82:85], v[26:29]
	v_exp_f32_e32 v116, v116
	v_mfma_f32_16x16x32_bf16 v[30:33], v[206:209], v[86:89], v[30:33]
	ds_read_b64_tr_b16 v[206:207], v245 offset:32768
	ds_read_b64_tr_b16 v[208:209], v245 offset:36864
	v_exp_f32_e32 v117, v117
	s_waitcnt lgkmcnt(10)
	v_mfma_f32_16x16x32_bf16 v[34:37], v[210:213], v[82:85], v[34:37]
	v_exp_f32_e32 v118, v118
	v_mfma_f32_16x16x32_bf16 v[38:41], v[210:213], v[86:89], v[38:41]
	ds_read_b64_tr_b16 v[210:211], v238 offset:40960
	ds_read_b64_tr_b16 v[212:213], v238 offset:45056
	v_exp_f32_e32 v119, v119
	s_waitcnt lgkmcnt(10)
	v_mfma_f32_16x16x32_bf16 v[42:45], v[214:217], v[82:85], v[42:45]
	v_exp_f32_e32 v120, v120
	v_mfma_f32_16x16x32_bf16 v[46:49], v[214:217], v[86:89], v[46:49]
	ds_read_b64_tr_b16 v[214:215], v239 offset:40960
	ds_read_b64_tr_b16 v[216:217], v239 offset:45056
	v_exp_f32_e32 v121, v121
	s_waitcnt lgkmcnt(10)
	v_mfma_f32_16x16x32_bf16 v[50:53], v[218:221], v[82:85], v[50:53]
	v_exp_f32_e32 v122, v122
	v_mfma_f32_16x16x32_bf16 v[54:57], v[218:221], v[86:89], v[54:57]
	ds_read_b64_tr_b16 v[218:219], v240 offset:40960
	ds_read_b64_tr_b16 v[220:221], v240 offset:45056
	v_exp_f32_e32 v123, v123
	s_waitcnt lgkmcnt(10)
	v_mfma_f32_16x16x32_bf16 v[58:61], v[222:225], v[82:85], v[58:61]
	v_exp_f32_e32 v124, v124
	v_mfma_f32_16x16x32_bf16 v[62:65], v[222:225], v[86:89], v[62:65]
	ds_read_b64_tr_b16 v[222:223], v241 offset:40960
	ds_read_b64_tr_b16 v[224:225], v241 offset:45056
	v_exp_f32_e32 v125, v125
	s_waitcnt lgkmcnt(10)
	v_mfma_f32_16x16x32_bf16 v[66:69], v[202:205], v[82:85], v[66:69]
	v_exp_f32_e32 v126, v126
	v_mfma_f32_16x16x32_bf16 v[70:73], v[202:205], v[86:89], v[70:73]
	ds_read_b64_tr_b16 v[202:203], v242 offset:40960
	ds_read_b64_tr_b16 v[204:205], v242 offset:45056
	v_exp_f32_e32 v127, v127
	s_waitcnt lgkmcnt(10)
; #define SBAR() __builtin_amdgcn_sched_barrier(0)
; __device__ __forceinline__ void finishSM(f32x16& p0, f32x16& p1, float& l_reg, bf16x8& pa0, bf16x8& pa1, bf16x8& pa2, bf16x8& pa3) {
;   for (int r = 0; r < 16; ++r) p1[r] = __builtin_amdgcn_exp2f(p1[r]);
;   float ps = 0; for (int r = 0; r < 16; ++r) ps += p0[r]; for (int r = 0; r < 16; ++r) ps += p1[r];
;   { auto rr = __builtin_amdgcn_permlane32_swap(__float_as_uint(ps), __float_as_uint(ps), false, false);
;     ps = __uint_as_float(rr[0]) + __uint_as_float(rr[1]); }
;   l_reg += ps;
;     ...
;   PK4(p0, 0, pa0); PK4(p0, 8, pa1); PK4(p1, 0, pa2); PK4(p1, 8, pa3);
;     ...
; }
; template <typename TQ> ...
;     ...
;   finishSM(pB0, pB1, l_reg, pa0, pa1, pa2, pa3); SBAR();
;   pv_d0(o, vb0 + (int)SHM_V, pa0, pa1, pa2, pa3);
	v_mfma_f32_16x16x32_bf16 v[74:77], v[206:209], v[82:85], v[74:77]
	v_exp_f32_e32 v128, v128
	v_mfma_f32_16x16x32_bf16 v[78:81], v[206:209], v[86:89], v[78:81]
	ds_read_b64_tr_b16 v[206:207], v243 offset:40960
	ds_read_b64_tr_b16 v[208:209], v243 offset:45056
	v_exp_f32_e32 v129, v129
	s_waitcnt lgkmcnt(10)
	v_mfma_f32_16x16x32_bf16 v[18:21], v[210:213], v[98:101], v[18:21]
	v_exp_f32_e32 v130, v130
	v_mfma_f32_16x16x32_bf16 v[22:25], v[210:213], v[102:105], v[22:25]
	ds_read_b64_tr_b16 v[210:211], v244 offset:40960
	ds_read_b64_tr_b16 v[212:213], v244 offset:45056
	v_exp_f32_e32 v131, v131
	s_waitcnt lgkmcnt(10)
	v_mfma_f32_16x16x32_bf16 v[26:29], v[214:217], v[98:101], v[26:29]
	v_exp_f32_e32 v132, v132
	v_mfma_f32_16x16x32_bf16 v[30:33], v[214:217], v[102:105], v[30:33]
	ds_read_b64_tr_b16 v[214:215], v245 offset:40960
	ds_read_b64_tr_b16 v[216:217], v245 offset:45056
	v_exp_f32_e32 v133, v133
	s_waitcnt lgkmcnt(10)
	v_mfma_f32_16x16x32_bf16 v[34:37], v[218:221], v[98:101], v[34:37]
	v_exp_f32_e32 v134, v134
	v_mfma_f32_16x16x32_bf16 v[38:41], v[218:221], v[102:105], v[38:41]
	v_exp_f32_e32 v135, v135
	s_waitcnt lgkmcnt(8)
	v_mfma_f32_16x16x32_bf16 v[42:45], v[222:225], v[98:101], v[42:45]
	v_exp_f32_e32 v136, v136
	v_mfma_f32_16x16x32_bf16 v[46:49], v[222:225], v[102:105], v[46:49]
	v_exp_f32_e32 v137, v137
	s_waitcnt lgkmcnt(6)
	v_mfma_f32_16x16x32_bf16 v[50:53], v[202:205], v[98:101], v[50:53]
	v_exp_f32_e32 v138, v138
	v_mfma_f32_16x16x32_bf16 v[54:57], v[202:205], v[102:105], v[54:57]
	v_exp_f32_e32 v139, v139
	s_waitcnt lgkmcnt(4)
	v_mfma_f32_16x16x32_bf16 v[58:61], v[206:209], v[98:101], v[58:61]
	v_exp_f32_e32 v140, v140
	v_mfma_f32_16x16x32_bf16 v[62:65], v[206:209], v[102:105], v[62:65]
	v_exp_f32_e32 v141, v141
	s_waitcnt lgkmcnt(2)
	v_mfma_f32_16x16x32_bf16 v[66:69], v[210:213], v[98:101], v[66:69]
	v_exp_f32_e32 v142, v142
	v_mfma_f32_16x16x32_bf16 v[70:73], v[210:213], v[102:105], v[70:73]
	v_exp_f32_e32 v143, v143
	s_waitcnt lgkmcnt(0)
	v_mfma_f32_16x16x32_bf16 v[74:77], v[214:217], v[98:101], v[74:77]
	v_exp_f32_e32 v144, v144
	v_mfma_f32_16x16x32_bf16 v[78:81], v[214:217], v[102:105], v[78:81]
	v_exp_f32_e32 v145, v145
	s_waitcnt vmcnt(0)
	v_add_f32_e32 v250, v114, v250
	v_add_f32_e32 v250, v115, v250
	v_add_f32_e32 v250, v116, v250
	v_add_f32_e32 v250, v117, v250
	v_add_f32_e32 v250, v122, v250
	v_add_f32_e32 v250, v123, v250
	v_add_f32_e32 v250, v124, v250
	v_add_f32_e32 v250, v125, v250
	v_cvt_pk_bf16_f32 v114, v114, v115
	v_cvt_pk_bf16_f32 v115, v116, v117
	v_cvt_pk_bf16_f32 v116, v122, v123
	v_cvt_pk_bf16_f32 v117, v124, v125
	v_add_f32_e32 v251, v118, v251
	v_add_f32_e32 v251, v119, v251
	v_add_f32_e32 v251, v120, v251
	v_add_f32_e32 v251, v121, v251
	v_add_f32_e32 v251, v126, v251
	v_add_f32_e32 v251, v127, v251
	v_add_f32_e32 v251, v128, v251
	v_add_f32_e32 v251, v129, v251
	v_cvt_pk_bf16_f32 v118, v118, v119
	v_cvt_pk_bf16_f32 v119, v120, v121
	v_cvt_pk_bf16_f32 v120, v126, v127
	v_cvt_pk_bf16_f32 v121, v128, v129
	v_add_f32_e32 v250, v130, v250
	v_add_f32_e32 v250, v131, v250
	v_add_f32_e32 v250, v132, v250
	v_add_f32_e32 v250, v133, v250
	v_add_f32_e32 v250, v138, v250
	v_add_f32_e32 v250, v139, v250
	v_add_f32_e32 v250, v140, v250
	v_add_f32_e32 v250, v141, v250
	v_cvt_pk_bf16_f32 v130, v130, v131
	v_cvt_pk_bf16_f32 v131, v132, v133
	v_cvt_pk_bf16_f32 v132, v138, v139
	v_cvt_pk_bf16_f32 v133, v140, v141
	v_add_f32_e32 v251, v134, v251
	v_add_f32_e32 v251, v135, v251
	v_add_f32_e32 v251, v136, v251
	v_add_f32_e32 v251, v137, v251
	v_add_f32_e32 v251, v142, v251
	v_add_f32_e32 v251, v143, v251
	v_add_f32_e32 v251, v144, v251
	v_add_f32_e32 v251, v145, v251
	v_cvt_pk_bf16_f32 v134, v134, v135
	v_cvt_pk_bf16_f32 v135, v136, v137
	v_cvt_pk_bf16_f32 v136, v142, v143
	v_cvt_pk_bf16_f32 v137, v144, v145
	ds_read_b64_tr_b16 v[202:203], v238 offset:49152
	ds_read_b64_tr_b16 v[204:205], v238 offset:53248
	ds_read_b64_tr_b16 v[206:207], v239 offset:49152
	ds_read_b64_tr_b16 v[208:209], v239 offset:53248
	ds_read_b64_tr_b16 v[210:211], v240 offset:49152
	ds_read_b64_tr_b16 v[212:213], v240 offset:53248
	ds_read_b64_tr_b16 v[214:215], v241 offset:49152
	ds_read_b64_tr_b16 v[216:217], v241 offset:53248
	ds_read_b64_tr_b16 v[218:219], v242 offset:49152
	ds_read_b64_tr_b16 v[220:221], v242 offset:53248
	ds_read_b64_tr_b16 v[222:223], v243 offset:49152
	ds_read_b64_tr_b16 v[224:225], v243 offset:53248
	s_waitcnt lgkmcnt(10)
	v_mfma_f32_16x16x32_bf16 v[18:21], v[202:205], v[114:117], v[18:21]
	v_mfma_f32_16x16x32_bf16 v[22:25], v[202:205], v[118:121], v[22:25]
	ds_read_b64_tr_b16 v[202:203], v244 offset:49152
	ds_read_b64_tr_b16 v[204:205], v244 offset:53248
	s_waitcnt lgkmcnt(10)
	v_mfma_f32_16x16x32_bf16 v[26:29], v[206:209], v[114:117], v[26:29]
	v_mfma_f32_16x16x32_bf16 v[30:33], v[206:209], v[118:121], v[30:33]
	ds_read_b64_tr_b16 v[206:207], v245 offset:49152
	ds_read_b64_tr_b16 v[208:209], v245 offset:53248
	s_waitcnt lgkmcnt(10)
	v_mfma_f32_16x16x32_bf16 v[34:37], v[210:213], v[114:117], v[34:37]
	v_mfma_f32_16x16x32_bf16 v[38:41], v[210:213], v[118:121], v[38:41]
	ds_read_b64_tr_b16 v[210:211], v238 offset:57344
	ds_read_b64_tr_b16 v[212:213], v238 offset:61440
	s_waitcnt lgkmcnt(10)
	v_mfma_f32_16x16x32_bf16 v[42:45], v[214:217], v[114:117], v[42:45]
	v_mfma_f32_16x16x32_bf16 v[46:49], v[214:217], v[118:121], v[46:49]
	ds_read_b64_tr_b16 v[214:215], v239 offset:57344
	ds_read_b64_tr_b16 v[216:217], v239 offset:61440
	s_waitcnt lgkmcnt(10)
	v_mfma_f32_16x16x32_bf16 v[50:53], v[218:221], v[114:117], v[50:53]
	v_mfma_f32_16x16x32_bf16 v[54:57], v[218:221], v[118:121], v[54:57]
	ds_read_b64_tr_b16 v[218:219], v240 offset:57344
	ds_read_b64_tr_b16 v[220:221], v240 offset:61440
	s_waitcnt lgkmcnt(10)
; #define SBAR() __builtin_amdgcn_sched_barrier(0)
; __device__ __forceinline__ int crow(int r, int hi) { return (r & 3) + 8 * (r >> 2) + 4 * hi; }
; template <typename TQ> ...
;     ...
;   finishSM(pB0, pB1, l_reg, pa0, pa1, pa2, pa3); SBAR();
;   pv_d0(o, vb0 + (int)SHM_V, pa0, pa1, pa2, pa3);
;   if (hi == 0) li_l[r32] = l_reg; asm volatile("s_waitcnt lgkmcnt(0)" ::: "memory");
;   float rli[16];
; #pragma unroll
;   for (int r = 0; r < 16; ++r) rli[r] = __builtin_amdgcn_rcpf(li_l[crow(r, hi)]);
;   int le = (int)(threadIdx.x & 63u); asm volatile("" : "+v"(le));
;   const int r32e = le & 31, hie = le >> 5;
;   bf16* Ow = Ob + (long)(wid * QBLK) * LDO;
; #pragma unroll
;   for (int r = 0; r < 16; ++r) { int orow = crow(r, hie);
;     for (int d0 = 0; d0 < 4; ++d0) Ow[(long)orow * LDO + d0 * 32 + r32e] = __float2bfloat16(o[d0][r] * rli[r]); }
; __global__ void __launch_bounds__(NTHR, 2) fwd_megakernel(KArgs a) {
;     ...
;         for (int i = 0; i < upb; ++i) {
;             const int unit = vcu * upb + i; if (unit >= 512) break;
;             const int grp = unit >> 7, rem = unit & 127, gq = rem >> 5, qb = rem & 31, b = grp >> 1, kvh = grp & 1, h = kvh * 4 + gq;
;             const size_t qoff = ((size_t)(b * SEQ + qb * 256)) * DM + h * 128, koff = (size_t)b * SKV * 256 + kvh * 128;
;             att::attn_dense_body<att::bf16>(Q + qoff, Kb + koff, Vb + koff, O + qoff, SKV, (char*)lds_raw, mC, a.g_q, (const float*)(ws + WS_ROPE), (const float*)(ws + WS_ROPE) + 4096, qb * 256);
;             __syncthreads();
;         }
	v_mfma_f32_16x16x32_bf16 v[58:61], v[222:225], v[114:117], v[58:61]
	v_mfma_f32_16x16x32_bf16 v[62:65], v[222:225], v[118:121], v[62:65]
	ds_read_b64_tr_b16 v[222:223], v241 offset:57344
	ds_read_b64_tr_b16 v[224:225], v241 offset:61440
	s_waitcnt lgkmcnt(10)
	v_mfma_f32_16x16x32_bf16 v[66:69], v[202:205], v[114:117], v[66:69]
	v_mfma_f32_16x16x32_bf16 v[70:73], v[202:205], v[118:121], v[70:73]
	ds_read_b64_tr_b16 v[202:203], v242 offset:57344
	ds_read_b64_tr_b16 v[204:205], v242 offset:61440
	s_waitcnt lgkmcnt(10)
	v_mfma_f32_16x16x32_bf16 v[74:77], v[206:209], v[114:117], v[74:77]
	v_mfma_f32_16x16x32_bf16 v[78:81], v[206:209], v[118:121], v[78:81]
	ds_read_b64_tr_b16 v[206:207], v243 offset:57344
	ds_read_b64_tr_b16 v[208:209], v243 offset:61440
	s_waitcnt lgkmcnt(10)
	v_mfma_f32_16x16x32_bf16 v[18:21], v[210:213], v[130:133], v[18:21]
	v_mfma_f32_16x16x32_bf16 v[22:25], v[210:213], v[134:137], v[22:25]
	ds_read_b64_tr_b16 v[210:211], v244 offset:57344
	ds_read_b64_tr_b16 v[212:213], v244 offset:61440
	s_waitcnt lgkmcnt(10)
	v_mfma_f32_16x16x32_bf16 v[26:29], v[214:217], v[130:133], v[26:29]
	v_mfma_f32_16x16x32_bf16 v[30:33], v[214:217], v[134:137], v[30:33]
	ds_read_b64_tr_b16 v[214:215], v245 offset:57344
	ds_read_b64_tr_b16 v[216:217], v245 offset:61440
	s_waitcnt lgkmcnt(10)
	v_mfma_f32_16x16x32_bf16 v[34:37], v[218:221], v[130:133], v[34:37]
	v_mfma_f32_16x16x32_bf16 v[38:41], v[218:221], v[134:137], v[38:41]
	s_waitcnt lgkmcnt(8)
	v_mfma_f32_16x16x32_bf16 v[42:45], v[222:225], v[130:133], v[42:45]
	v_mfma_f32_16x16x32_bf16 v[46:49], v[222:225], v[134:137], v[46:49]
	s_waitcnt lgkmcnt(6)
	v_mfma_f32_16x16x32_bf16 v[50:53], v[202:205], v[130:133], v[50:53]
	v_mfma_f32_16x16x32_bf16 v[54:57], v[202:205], v[134:137], v[54:57]
	s_waitcnt lgkmcnt(4)
	v_mfma_f32_16x16x32_bf16 v[58:61], v[206:209], v[130:133], v[58:61]
	v_mfma_f32_16x16x32_bf16 v[62:65], v[206:209], v[134:137], v[62:65]
	s_waitcnt lgkmcnt(2)
	v_mfma_f32_16x16x32_bf16 v[66:69], v[210:213], v[130:133], v[66:69]
	v_mfma_f32_16x16x32_bf16 v[70:73], v[210:213], v[134:137], v[70:73]
	s_waitcnt lgkmcnt(0)
	v_mfma_f32_16x16x32_bf16 v[74:77], v[214:217], v[130:133], v[74:77]
	v_mfma_f32_16x16x32_bf16 v[78:81], v[214:217], v[134:137], v[78:81]
	s_setprio 0
	ds_swizzle_b32 v6, v250 offset:swizzle(SWAP,16)
	s_waitcnt lgkmcnt(0)
	v_add_f32_e32 v250, v250, v6
	v_mov_b32_e32 v6, v250
	s_nop 1
	v_permlane32_swap_b32_e32 v250, v6
	v_add_f32_e32 v250, v250, v6
	v_rcp_f32_e32 v250, v250
	ds_swizzle_b32 v6, v251 offset:swizzle(SWAP,16)
	s_waitcnt lgkmcnt(0)
	v_add_f32_e32 v251, v251, v6
	v_mov_b32_e32 v6, v251
	s_nop 1
	v_permlane32_swap_b32_e32 v251, v6
	v_add_f32_e32 v251, v251, v6
	v_rcp_f32_e32 v251, v251
	s_add_u32 s12, s71, s48
	s_addc_u32 s13, s72, s49
	v_add_u32_e32 v201, s52, v16
	v_lshlrev_b32_e32 v201, 11, v201
	v_lshl_or_b32 v7, v17, 3, v201
	v_add_u32_e32 v200, 0x8000, v7
	v_mul_f32_e32 v18, v18, v250
	v_mul_f32_e32 v19, v19, v250
	v_mul_f32_e32 v20, v20, v250
	v_mul_f32_e32 v21, v21, v250
	v_cvt_pk_bf16_f32 v18, v18, v19
	v_cvt_pk_bf16_f32 v19, v20, v21
	global_store_dwordx2 v7, v[18:19], s[12:13] offset:0
	v_mul_f32_e32 v22, v22, v251
	v_mul_f32_e32 v23, v23, v251
	v_mul_f32_e32 v24, v24, v251
	v_mul_f32_e32 v25, v25, v251
	v_cvt_pk_bf16_f32 v22, v22, v23
	v_cvt_pk_bf16_f32 v23, v24, v25
	global_store_dwordx2 v200, v[22:23], s[12:13] offset:0
	v_mul_f32_e32 v26, v26, v250
	v_mul_f32_e32 v27, v27, v250
	v_mul_f32_e32 v28, v28, v250
	v_mul_f32_e32 v29, v29, v250
	v_cvt_pk_bf16_f32 v26, v26, v27
	v_cvt_pk_bf16_f32 v27, v28, v29
	global_store_dwordx2 v7, v[26:27], s[12:13] offset:32
	v_mul_f32_e32 v30, v30, v251
	v_mul_f32_e32 v31, v31, v251
	v_mul_f32_e32 v32, v32, v251
	v_mul_f32_e32 v33, v33, v251
	v_cvt_pk_bf16_f32 v30, v30, v31
	v_cvt_pk_bf16_f32 v31, v32, v33
	global_store_dwordx2 v200, v[30:31], s[12:13] offset:32
	v_mul_f32_e32 v34, v34, v250
	v_mul_f32_e32 v35, v35, v250
	v_mul_f32_e32 v36, v36, v250
	v_mul_f32_e32 v37, v37, v250
	v_cvt_pk_bf16_f32 v34, v34, v35
	v_cvt_pk_bf16_f32 v35, v36, v37
	global_store_dwordx2 v7, v[34:35], s[12:13] offset:64
	v_mul_f32_e32 v38, v38, v251
	v_mul_f32_e32 v39, v39, v251
	v_mul_f32_e32 v40, v40, v251
	v_mul_f32_e32 v41, v41, v251
	v_cvt_pk_bf16_f32 v38, v38, v39
	v_cvt_pk_bf16_f32 v39, v40, v41
	global_store_dwordx2 v200, v[38:39], s[12:13] offset:64
	v_mul_f32_e32 v42, v42, v250
	v_mul_f32_e32 v43, v43, v250
	v_mul_f32_e32 v44, v44, v250
	v_mul_f32_e32 v45, v45, v250
	v_cvt_pk_bf16_f32 v42, v42, v43
	v_cvt_pk_bf16_f32 v43, v44, v45
	global_store_dwordx2 v7, v[42:43], s[12:13] offset:96
	v_mul_f32_e32 v46, v46, v251
	v_mul_f32_e32 v47, v47, v251
	v_mul_f32_e32 v48, v48, v251
	v_mul_f32_e32 v49, v49, v251
	v_cvt_pk_bf16_f32 v46, v46, v47
	v_cvt_pk_bf16_f32 v47, v48, v49
	global_store_dwordx2 v200, v[46:47], s[12:13] offset:96
	v_mul_f32_e32 v50, v50, v250
	v_mul_f32_e32 v51, v51, v250
	v_mul_f32_e32 v52, v52, v250
	v_mul_f32_e32 v53, v53, v250
	v_cvt_pk_bf16_f32 v50, v50, v51
	v_cvt_pk_bf16_f32 v51, v52, v53
	global_store_dwordx2 v7, v[50:51], s[12:13] offset:128
	v_mul_f32_e32 v54, v54, v251
	v_mul_f32_e32 v55, v55, v251
	v_mul_f32_e32 v56, v56, v251
	v_mul_f32_e32 v57, v57, v251
	v_cvt_pk_bf16_f32 v54, v54, v55
	v_cvt_pk_bf16_f32 v55, v56, v57
	global_store_dwordx2 v200, v[54:55], s[12:13] offset:128
	v_mul_f32_e32 v58, v58, v250
	v_mul_f32_e32 v59, v59, v250
	v_mul_f32_e32 v60, v60, v250
	v_mul_f32_e32 v61, v61, v250
	v_cvt_pk_bf16_f32 v58, v58, v59
	v_cvt_pk_bf16_f32 v59, v60, v61
	global_store_dwordx2 v7, v[58:59], s[12:13] offset:160
	v_mul_f32_e32 v62, v62, v251
	v_mul_f32_e32 v63, v63, v251
	v_mul_f32_e32 v64, v64, v251
	v_mul_f32_e32 v65, v65, v251
	v_cvt_pk_bf16_f32 v62, v62, v63
	v_cvt_pk_bf16_f32 v63, v64, v65
	global_store_dwordx2 v200, v[62:63], s[12:13] offset:160
	v_mul_f32_e32 v66, v66, v250
	v_mul_f32_e32 v67, v67, v250
	v_mul_f32_e32 v68, v68, v250
	v_mul_f32_e32 v69, v69, v250
	v_cvt_pk_bf16_f32 v66, v66, v67
	v_cvt_pk_bf16_f32 v67, v68, v69
	global_store_dwordx2 v7, v[66:67], s[12:13] offset:192
	v_mul_f32_e32 v70, v70, v251
	v_mul_f32_e32 v71, v71, v251
	v_mul_f32_e32 v72, v72, v251
	v_mul_f32_e32 v73, v73, v251
	v_cvt_pk_bf16_f32 v70, v70, v71
	v_cvt_pk_bf16_f32 v71, v72, v73
	global_store_dwordx2 v200, v[70:71], s[12:13] offset:192
	v_mul_f32_e32 v74, v74, v250
	v_mul_f32_e32 v75, v75, v250
	v_mul_f32_e32 v76, v76, v250
	v_mul_f32_e32 v77, v77, v250
	v_cvt_pk_bf16_f32 v74, v74, v75
	v_cvt_pk_bf16_f32 v75, v76, v77
	global_store_dwordx2 v7, v[74:75], s[12:13] offset:224
	v_mul_f32_e32 v78, v78, v251
	v_mul_f32_e32 v79, v79, v251
	v_mul_f32_e32 v80, v80, v251
	v_mul_f32_e32 v81, v81, v251
	v_cvt_pk_bf16_f32 v78, v78, v79
	v_cvt_pk_bf16_f32 v79, v80, v81
	global_store_dwordx2 v200, v[78:79], s[12:13] offset:224
	s_add_i32 s74, s74, 1
	s_add_i32 s94, s94, 1
	s_cmp_eq_u32 s74, s66
	s_cselect_b64 s[0:1], -1, 0
	s_barrier
	s_branch .LBB0_818
